# speedup vs baseline: 1.0114x; 1.0054x over previous
; #define G_STAGE(bufoff, gbase, voff) do { _Pragma("unroll") for (int _i = 0; _i < 2; ++_i) \
;         __builtin_amdgcn_global_load_lds((const unsigned*)((const char*)(gbase) + (voff)[_i]), (LAS unsigned*)(lds + (bufoff) + ldsw + _i * 8192), 16, 0, 0); } while (0)
; #define G_LDA(dst, b, h) do { _Pragma("unroll") for (int m = 0; m < 4; ++m) _Pragma("unroll") for (int k = 0; k < 2; ++k) dst[m][k] = *(const LAS bf16x8*)(lds + G_SA(b, h) + aoff + m * 2048 + k * 1024); } while (0)
; #define G_LDB(dst, b, h) do { _Pragma("unroll") for (int n = 0; n < 2; ++n) _Pragma("unroll") for (int k = 0; k < 2; ++k) dst[n][k] = *(const LAS bf16x8*)(lds + G_SB(b, h) + boff + n * 2048 + k * 1024); } while (0)
; #define G_MMA(ai, bj, At, Bt) do { __builtin_amdgcn_s_setprio(1); _Pragma("unroll") for (int m = 0; m < 4; ++m) _Pragma("unroll") for (int n = 0; n < 2; ++n) _Pragma("unroll") for (int k = 0; k < 2; ++k) \
;         acc[ai][bj][m][n] = __builtin_amdgcn_mfma_f32_16x16x32_bf16(Bt[n][k], At[m][k], acc[ai][bj][m][n], 0, 0, 0); __builtin_amdgcn_s_setprio(0); } while (0)
; #define G_WAIT_L(n) asm volatile("s_waitcnt lgkmcnt(" #n ")" ::: "memory")
; #define G_BAR __builtin_amdgcn_s_barrier()
; #define G_SCHED __builtin_amdgcn_sched_barrier(0)
;   DI const char* aptr(const Unit& u) const { return (const char*)(h + (size_t)u.pm * 256 * DM); }
; template <class J>
; DI void gemm_phase(LAS unsigned char* lds, const J& job) {
;     ...
;     const bool has_next = job.next(ui + 1, nxt);
;     const char* nA = has_next ? job.aptr(nxt) : cA; const char* nB = has_next ? job.bptr(nxt) : cB;
;     for (int t = 0; t < nt; t += 2) {
;       const bool last = (t == nt - 2);
;       const char* a1 = cA + G_KT(t + 1);
;       const char* a2 = last ? nA + G_KT(0) : cA + G_KT(t + 2); const char* b2 = last ? nB + G_KT(0) : cB + G_KT(t + 2);
;       const char* a3 = last ? nA + G_KT(1) : cA + G_KT(t + 3); const char* b3 = last ? nB + G_KT(1) : cB + G_KT(t + 3);
;       G_LDB(B0, 0, 0); G_SCHED; G_LDA(At, 0, 0); G_STAGE(G_SA(1, 1), a1 + hstepA, voffA);
;       G_WAIT_L(8); G_BAR; G_WAIT_L(0); G_MMA(0, 0, At, B0); G_BAR; G_SCHED;
;       G_LDB(B1, 0, 1); G_STAGE(G_SB(0, 0), b2, voffB);
;       G_BAR; G_WAIT_L(0); G_MMA(0, 1, At, B1); G_BAR;
;       G_LDA(At, 0, 1); G_STAGE(G_SA(0, 0), a2, voffA);
;       G_BAR; G_WAIT_L(0); G_MMA(1, 0, At, B0); G_BAR; G_SCHED;
.LBB0_42:
	s_add_i32 s1, s57, 0xffffff80
	s_and_b32 s0, s44, 0xf80
	s_and_b32 s1, s1, 0xf00
	s_add_u32 s2, s70, s1
	s_addc_u32 s72, s71, 0
	s_add_u32 s1, s68, s1
	s_addc_u32 s73, s69, 0
	s_and_b32 s74, s57, 0xf80
	s_add_u32 s80, s70, s74
	s_addc_u32 s75, s71, 0
	s_add_u32 s54, s68, s74
	s_addc_u32 s55, s69, 0
	s_cmp_eq_u32 s7, 28
	s_cselect_b32 s77, vcc_lo, s72
	s_cselect_b32 s76, s47, s2
	s_cselect_b32 s79, s33, s73
	s_cselect_b32 s78, vcc_hi, s1
	s_cselect_b32 s75, s4, s75
	s_cselect_b32 s74, s97, s80
	s_cselect_b32 s73, s6, s55
	s_cselect_b32 s72, s5, s54
	s_add_i32 s2, s84, 0x100
	v_add_u32_e32 v140, s2, v162
	ds_read_b128 v[128:131], v140
	ds_read_b128 v[132:135], v140 offset:1024
	ds_read_b128 v[136:139], v140 offset:2048
	ds_read_b128 v[140:143], v140 offset:3072
	s_add_u32 s0, s21, s0
	s_addc_u32 s1, s23, 0
	v_lshl_add_u64 v[158:159], s[0:1], 0, v[148:149]
	s_add_i32 m0, s25, 0xc000
	ds_read_b128 v[154:157], v163
	ds_read_b128 v[164:167], v163 offset:1024
	ds_read_b128 v[168:171], v163 offset:2048
	ds_read_b128 v[172:175], v163 offset:3072
	ds_read_b128 v[176:179], v163 offset:4096
	ds_read_b128 v[180:183], v163 offset:5120
	ds_read_b128 v[184:187], v163 offset:6144
	ds_read_b128 v[188:191], v163 offset:7168
	global_load_lds_dwordx4 v[158:159], off
	v_lshl_add_u64 v[158:159], s[0:1], 0, v[150:151]
	s_add_i32 m0, s25, 0xe000
	s_nop 0
	global_load_lds_dwordx4 v[158:159], off
	s_waitcnt lgkmcnt(8)
	s_barrier
	s_waitcnt lgkmcnt(0)
	v_mfma_f32_16x16x32_bf16 v[124:127], v[128:131], v[154:157], v[124:127]
	v_mfma_f32_16x16x32_bf16 v[120:123], v[136:139], v[154:157], v[120:123]
	v_mfma_f32_16x16x32_bf16 v[108:111], v[128:131], v[168:171], v[108:111]
	v_mfma_f32_16x16x32_bf16 v[104:107], v[136:139], v[168:171], v[104:107]
	v_mfma_f32_16x16x32_bf16 v[92:95], v[128:131], v[176:179], v[92:95]
	v_mfma_f32_16x16x32_bf16 v[88:91], v[136:139], v[176:179], v[88:91]
	v_mfma_f32_16x16x32_bf16 v[76:79], v[128:131], v[184:187], v[76:79]
	v_mfma_f32_16x16x32_bf16 v[72:75], v[136:139], v[184:187], v[72:75]
	v_mfma_f32_16x16x32_bf16 v[124:127], v[132:135], v[164:167], v[124:127]
	v_mfma_f32_16x16x32_bf16 v[120:123], v[140:143], v[164:167], v[120:123]
	v_mfma_f32_16x16x32_bf16 v[108:111], v[132:135], v[172:175], v[108:111]
	v_mfma_f32_16x16x32_bf16 v[104:107], v[140:143], v[172:175], v[104:107]
	v_mfma_f32_16x16x32_bf16 v[92:95], v[132:135], v[180:183], v[92:95]
	v_mfma_f32_16x16x32_bf16 v[88:91], v[140:143], v[180:183], v[88:91]
	v_mfma_f32_16x16x32_bf16 v[76:79], v[132:135], v[188:191], v[76:79]
	v_mfma_f32_16x16x32_bf16 v[72:75], v[140:143], v[188:191], v[72:75]
	s_barrier
	s_add_i32 s54, s85, 0x100
	v_add_u32_e32 v158, s54, v162
	s_add_i32 s0, s2, s14
	ds_read_b128 v[192:195], v158
	ds_read_b128 v[196:199], v158 offset:1024
	ds_read_b128 v[200:203], v158 offset:2048
	ds_read_b128 v[204:207], v158 offset:3072
	v_lshl_add_u64 v[158:159], s[78:79], 0, v[146:147]
	s_mov_b32 m0, s0
	s_nop 0
	global_load_lds_dwordx4 v[158:159], off
	v_lshl_add_u64 v[158:159], s[78:79], 0, v[152:153]
	s_add_i32 m0, s0, 0x2000
	s_nop 0
	global_load_lds_dwordx4 v[158:159], off
	s_barrier
	s_waitcnt lgkmcnt(0)
	v_mfma_f32_16x16x32_bf16 v[116:119], v[192:195], v[154:157], v[116:119]
	v_mfma_f32_16x16x32_bf16 v[112:115], v[200:203], v[154:157], v[112:115]
	v_mfma_f32_16x16x32_bf16 v[100:103], v[192:195], v[168:171], v[100:103]
	v_mfma_f32_16x16x32_bf16 v[96:99], v[200:203], v[168:171], v[96:99]
	v_mfma_f32_16x16x32_bf16 v[84:87], v[192:195], v[176:179], v[84:87]
	v_mfma_f32_16x16x32_bf16 v[80:83], v[200:203], v[176:179], v[80:83]
	v_mfma_f32_16x16x32_bf16 v[68:71], v[192:195], v[184:187], v[68:71]
	v_mfma_f32_16x16x32_bf16 v[64:67], v[200:203], v[184:187], v[64:67]
	v_mfma_f32_16x16x32_bf16 v[116:119], v[196:199], v[164:167], v[116:119]
	v_mfma_f32_16x16x32_bf16 v[112:115], v[204:207], v[164:167], v[112:115]
	v_mfma_f32_16x16x32_bf16 v[100:103], v[196:199], v[172:175], v[100:103]
	v_mfma_f32_16x16x32_bf16 v[96:99], v[204:207], v[172:175], v[96:99]
	v_mfma_f32_16x16x32_bf16 v[84:87], v[196:199], v[180:183], v[84:87]
	v_mfma_f32_16x16x32_bf16 v[80:83], v[204:207], v[180:183], v[80:83]
	v_mfma_f32_16x16x32_bf16 v[68:71], v[196:199], v[188:191], v[68:71]
	v_mfma_f32_16x16x32_bf16 v[64:67], v[204:207], v[188:191], v[64:67]
	s_mov_b32 m0, s25
	v_lshl_add_u64 v[158:159], s[76:77], 0, v[148:149]
	s_barrier
	ds_read_b128 v[154:157], v163 offset:16384
	ds_read_b128 v[164:167], v163 offset:17408
	ds_read_b128 v[168:171], v163 offset:18432
	ds_read_b128 v[172:175], v163 offset:19456
	ds_read_b128 v[176:179], v163 offset:20480
	ds_read_b128 v[180:183], v163 offset:21504
	ds_read_b128 v[184:187], v163 offset:22528
	ds_read_b128 v[188:191], v163 offset:23552
	global_load_lds_dwordx4 v[158:159], off
	v_lshl_add_u64 v[158:159], s[76:77], 0, v[150:151]
	s_mov_b32 m0, s36
	s_nop 0
	global_load_lds_dwordx4 v[158:159], off
	s_barrier
	s_waitcnt lgkmcnt(0)
	v_mfma_f32_16x16x32_bf16 v[60:63], v[128:131], v[154:157], v[60:63]
	v_mfma_f32_16x16x32_bf16 v[56:59], v[136:139], v[154:157], v[56:59]
	v_mfma_f32_16x16x32_bf16 v[44:47], v[128:131], v[168:171], v[44:47]
	v_mfma_f32_16x16x32_bf16 v[40:43], v[136:139], v[168:171], v[40:43]
	v_mfma_f32_16x16x32_bf16 v[28:31], v[128:131], v[176:179], v[28:31]
	v_mfma_f32_16x16x32_bf16 v[24:27], v[136:139], v[176:179], v[24:27]
	v_mfma_f32_16x16x32_bf16 v[20:23], v[128:131], v[184:187], v[20:23]
	v_mfma_f32_16x16x32_bf16 v[12:15], v[136:139], v[184:187], v[12:15]
	v_mfma_f32_16x16x32_bf16 v[60:63], v[132:135], v[164:167], v[60:63]
	v_mfma_f32_16x16x32_bf16 v[56:59], v[140:143], v[164:167], v[56:59]
	v_mfma_f32_16x16x32_bf16 v[44:47], v[132:135], v[172:175], v[44:47]
	v_mfma_f32_16x16x32_bf16 v[40:43], v[140:143], v[172:175], v[40:43]
	v_mfma_f32_16x16x32_bf16 v[28:31], v[132:135], v[180:183], v[28:31]
	v_mfma_f32_16x16x32_bf16 v[24:27], v[140:143], v[180:183], v[24:27]
	v_mfma_f32_16x16x32_bf16 v[20:23], v[132:135], v[188:191], v[20:23]
	v_mfma_f32_16x16x32_bf16 v[12:15], v[140:143], v[188:191], v[12:15]
	s_barrier
; #define G_STAGE(bufoff, gbase, voff) do { _Pragma("unroll") for (int _i = 0; _i < 2; ++_i) \
;         __builtin_amdgcn_global_load_lds((const unsigned*)((const char*)(gbase) + (voff)[_i]), (LAS unsigned*)(lds + (bufoff) + ldsw + _i * 8192), 16, 0, 0); } while (0)
; #define G_LDA(dst, b, h) do { _Pragma("unroll") for (int m = 0; m < 4; ++m) _Pragma("unroll") for (int k = 0; k < 2; ++k) dst[m][k] = *(const LAS bf16x8*)(lds + G_SA(b, h) + aoff + m * 2048 + k * 1024); } while (0)
; #define G_LDB(dst, b, h) do { _Pragma("unroll") for (int n = 0; n < 2; ++n) _Pragma("unroll") for (int k = 0; k < 2; ++k) dst[n][k] = *(const LAS bf16x8*)(lds + G_SB(b, h) + boff + n * 2048 + k * 1024); } while (0)
; #define G_MMA(ai, bj, At, Bt) do { __builtin_amdgcn_s_setprio(1); _Pragma("unroll") for (int m = 0; m < 4; ++m) _Pragma("unroll") for (int n = 0; n < 2; ++n) _Pragma("unroll") for (int k = 0; k < 2; ++k) \
;         acc[ai][bj][m][n] = __builtin_amdgcn_mfma_f32_16x16x32_bf16(Bt[n][k], At[m][k], acc[ai][bj][m][n], 0, 0, 0); __builtin_amdgcn_s_setprio(0); } while (0)
; #define G_WAIT_V(n) asm volatile("s_waitcnt vmcnt(" #n ")" ::: "memory")
; #define G_WAIT_L(n) asm volatile("s_waitcnt lgkmcnt(" #n ")" ::: "memory")
; #define G_BAR __builtin_amdgcn_s_barrier()
; #define G_SCHED __builtin_amdgcn_sched_barrier(0)
; template <class J>
; DI void gemm_phase(LAS unsigned char* lds, const J& job) {
;     ...
;       G_STAGE(G_SB(0, 1), b2 + hstepB, voffB);
;       G_WAIT_V(6); G_BAR; G_MMA(1, 1, At, B1); G_BAR;
;       G_LDB(B0, 1, 0); G_SCHED; G_LDA(At, 1, 0); G_STAGE(G_SA(0, 1), a2 + hstepA, voffA);
;       G_WAIT_L(8); G_BAR; G_WAIT_L(0); G_MMA(0, 0, At, B0); G_BAR; G_SCHED;
;       G_LDB(B1, 1, 1); G_STAGE(G_SB(1, 0), b3, voffB);
;       G_BAR; G_WAIT_L(0); G_MMA(0, 1, At, B1); G_BAR;
;       G_LDA(At, 1, 1); G_STAGE(G_SA(1, 0), a3, voffA);
	s_add_u32 s0, s78, 0x80000
	s_addc_u32 s1, s79, 0
	s_add_i32 s2, s54, s14
	v_lshl_add_u64 v[128:129], s[0:1], 0, v[146:147]
	s_mov_b32 m0, s2
	s_nop 0
	global_load_lds_dwordx4 v[128:129], off
	v_lshl_add_u64 v[128:129], s[0:1], 0, v[152:153]
	s_add_i32 m0, s2, 0x2000
	s_nop 0
	global_load_lds_dwordx4 v[128:129], off
	s_waitcnt vmcnt(6)
	s_barrier
	v_mfma_f32_16x16x32_bf16 v[52:55], v[192:195], v[154:157], v[52:55]
	v_mfma_f32_16x16x32_bf16 v[48:51], v[200:203], v[154:157], v[48:51]
	v_mfma_f32_16x16x32_bf16 v[36:39], v[192:195], v[168:171], v[36:39]
	v_mfma_f32_16x16x32_bf16 v[32:35], v[200:203], v[168:171], v[32:35]
	v_mfma_f32_16x16x32_bf16 v[16:19], v[192:195], v[176:179], v[16:19]
	v_mfma_f32_16x16x32_bf16 v[8:11], v[200:203], v[176:179], v[8:11]
	v_mfma_f32_16x16x32_bf16 v[4:7], v[192:195], v[184:187], v[4:7]
	v_mfma_f32_16x16x32_bf16 v[0:3], v[200:203], v[184:187], v[0:3]
	v_mfma_f32_16x16x32_bf16 v[52:55], v[196:199], v[164:167], v[52:55]
	v_mfma_f32_16x16x32_bf16 v[48:51], v[204:207], v[164:167], v[48:51]
	v_mfma_f32_16x16x32_bf16 v[36:39], v[196:199], v[172:175], v[36:39]
	v_mfma_f32_16x16x32_bf16 v[32:35], v[204:207], v[172:175], v[32:35]
	v_mfma_f32_16x16x32_bf16 v[16:19], v[196:199], v[180:183], v[16:19]
	v_mfma_f32_16x16x32_bf16 v[8:11], v[204:207], v[180:183], v[8:11]
	v_mfma_f32_16x16x32_bf16 v[4:7], v[196:199], v[188:191], v[4:7]
	v_mfma_f32_16x16x32_bf16 v[0:3], v[204:207], v[188:191], v[0:3]
	s_add_i32 s2, s88, 0x100
	v_add_u32_e32 v140, s2, v162
	s_barrier
	ds_read_b128 v[128:131], v140
	ds_read_b128 v[132:135], v140 offset:1024
	ds_read_b128 v[136:139], v140 offset:2048
	ds_read_b128 v[140:143], v140 offset:3072
	s_add_u32 s0, s76, 0x80000
	s_addc_u32 s1, s77, 0
	s_mov_b32 m0, s37
	v_lshl_add_u64 v[158:159], s[0:1], 0, v[148:149]
	ds_read_b128 v[154:157], v163 offset:32768
	ds_read_b128 v[164:167], v163 offset:33792
	ds_read_b128 v[168:171], v163 offset:34816
	ds_read_b128 v[172:175], v163 offset:35840
	ds_read_b128 v[176:179], v163 offset:36864
	ds_read_b128 v[180:183], v163 offset:37888
	ds_read_b128 v[184:187], v163 offset:38912
	ds_read_b128 v[188:191], v163 offset:39936
	global_load_lds_dwordx4 v[158:159], off
	v_lshl_add_u64 v[158:159], s[0:1], 0, v[150:151]
	s_mov_b32 m0, s38
	s_nop 0
	global_load_lds_dwordx4 v[158:159], off
	s_waitcnt lgkmcnt(8)
	s_barrier
	s_waitcnt lgkmcnt(0)
	v_mfma_f32_16x16x32_bf16 v[124:127], v[128:131], v[154:157], v[124:127]
	v_mfma_f32_16x16x32_bf16 v[120:123], v[136:139], v[154:157], v[120:123]
	v_mfma_f32_16x16x32_bf16 v[108:111], v[128:131], v[168:171], v[108:111]
	v_mfma_f32_16x16x32_bf16 v[104:107], v[136:139], v[168:171], v[104:107]
	v_mfma_f32_16x16x32_bf16 v[92:95], v[128:131], v[176:179], v[92:95]
	v_mfma_f32_16x16x32_bf16 v[88:91], v[136:139], v[176:179], v[88:91]
	v_mfma_f32_16x16x32_bf16 v[76:79], v[128:131], v[184:187], v[76:79]
	v_mfma_f32_16x16x32_bf16 v[72:75], v[136:139], v[184:187], v[72:75]
	v_mfma_f32_16x16x32_bf16 v[124:127], v[132:135], v[164:167], v[124:127]
	v_mfma_f32_16x16x32_bf16 v[120:123], v[140:143], v[164:167], v[120:123]
	v_mfma_f32_16x16x32_bf16 v[108:111], v[132:135], v[172:175], v[108:111]
	v_mfma_f32_16x16x32_bf16 v[104:107], v[140:143], v[172:175], v[104:107]
	v_mfma_f32_16x16x32_bf16 v[92:95], v[132:135], v[180:183], v[92:95]
	v_mfma_f32_16x16x32_bf16 v[88:91], v[140:143], v[180:183], v[88:91]
	v_mfma_f32_16x16x32_bf16 v[76:79], v[132:135], v[188:191], v[76:79]
	v_mfma_f32_16x16x32_bf16 v[72:75], v[140:143], v[188:191], v[72:75]
	s_barrier
	s_add_i32 s54, s89, 0x100
	v_add_u32_e32 v158, s54, v162
	s_add_i32 s0, s2, s14
	ds_read_b128 v[192:195], v158
	ds_read_b128 v[196:199], v158 offset:1024
	ds_read_b128 v[200:203], v158 offset:2048
	ds_read_b128 v[204:207], v158 offset:3072
	v_lshl_add_u64 v[158:159], s[72:73], 0, v[146:147]
	s_mov_b32 m0, s0
	s_nop 0
	global_load_lds_dwordx4 v[158:159], off
	v_lshl_add_u64 v[158:159], s[72:73], 0, v[152:153]
	s_add_i32 m0, s0, 0x2000
	s_nop 0
	global_load_lds_dwordx4 v[158:159], off
	s_barrier
	s_waitcnt lgkmcnt(0)
	v_mfma_f32_16x16x32_bf16 v[116:119], v[192:195], v[154:157], v[116:119]
	v_mfma_f32_16x16x32_bf16 v[112:115], v[200:203], v[154:157], v[112:115]
	v_mfma_f32_16x16x32_bf16 v[100:103], v[192:195], v[168:171], v[100:103]
	v_mfma_f32_16x16x32_bf16 v[96:99], v[200:203], v[168:171], v[96:99]
	v_mfma_f32_16x16x32_bf16 v[84:87], v[192:195], v[176:179], v[84:87]
	v_mfma_f32_16x16x32_bf16 v[80:83], v[200:203], v[176:179], v[80:83]
	v_mfma_f32_16x16x32_bf16 v[68:71], v[192:195], v[184:187], v[68:71]
	v_mfma_f32_16x16x32_bf16 v[64:67], v[200:203], v[184:187], v[64:67]
	v_mfma_f32_16x16x32_bf16 v[116:119], v[196:199], v[164:167], v[116:119]
	v_mfma_f32_16x16x32_bf16 v[112:115], v[204:207], v[164:167], v[112:115]
	v_mfma_f32_16x16x32_bf16 v[100:103], v[196:199], v[172:175], v[100:103]
	v_mfma_f32_16x16x32_bf16 v[96:99], v[204:207], v[172:175], v[96:99]
	v_mfma_f32_16x16x32_bf16 v[84:87], v[196:199], v[180:183], v[84:87]
	v_mfma_f32_16x16x32_bf16 v[80:83], v[204:207], v[180:183], v[80:83]
	v_mfma_f32_16x16x32_bf16 v[68:71], v[196:199], v[188:191], v[68:71]
	v_mfma_f32_16x16x32_bf16 v[64:67], v[204:207], v[188:191], v[64:67]
	s_mov_b32 m0, s87
	v_lshl_add_u64 v[158:159], s[74:75], 0, v[148:149]
	s_barrier
; #define G_STAGE(bufoff, gbase, voff) do { _Pragma("unroll") for (int _i = 0; _i < 2; ++_i) \
;         __builtin_amdgcn_global_load_lds((const unsigned*)((const char*)(gbase) + (voff)[_i]), (LAS unsigned*)(lds + (bufoff) + ldsw + _i * 8192), 16, 0, 0); } while (0)
; #define G_MMA(ai, bj, At, Bt) do { __builtin_amdgcn_s_setprio(1); _Pragma("unroll") for (int m = 0; m < 4; ++m) _Pragma("unroll") for (int n = 0; n < 2; ++n) _Pragma("unroll") for (int k = 0; k < 2; ++k) \
;         acc[ai][bj][m][n] = __builtin_amdgcn_mfma_f32_16x16x32_bf16(Bt[n][k], At[m][k], acc[ai][bj][m][n], 0, 0, 0); __builtin_amdgcn_s_setprio(0); } while (0)
; #define G_WAIT_V(n) asm volatile("s_waitcnt vmcnt(" #n ")" ::: "memory")
; #define G_WAIT_L(n) asm volatile("s_waitcnt lgkmcnt(" #n ")" ::: "memory")
; #define G_BAR __builtin_amdgcn_s_barrier()
; #define G_SCHED __builtin_amdgcn_sched_barrier(0)
; template <class J>
; DI void gemm_phase(LAS unsigned char* lds, const J& job) {
;     ...
;       G_BAR; G_WAIT_L(0); G_MMA(1, 0, At, B0); G_BAR; G_SCHED;
;       G_STAGE(G_SB(1, 1), b3 + hstepB, voffB);
;       G_WAIT_V(6); G_BAR; G_MMA(1, 1, At, B1); G_BAR;
;     }
;   DI void epi(const Acc& acc, const Unit& u, int wr, int wc, int fr, int fq) const {
; #pragma unroll
;     for (int ai = 0; ai < 2; ++ai) {
;       f32x4 res[4][2][2];
; #pragma unroll
;       for (int m = 0; m < 4; ++m) {
;         const int row = u.pm * 256 + ai * HALF + wr * 64 + m * 16 + fr;
;         const float* src = (l == 0) ? xp + (size_t)row * DM : out + (size_t)row * DM;
; #pragma unroll
;         for (int bj = 0; bj < 2; ++bj) { const int col = u.pn * 256 + bj * HALF + wc * 32 + 8 * fq; res[m][bj][0] = *(const f32x4*)(src + col); res[m][bj][1] = *(const f32x4*)(src + col + 4); }
;       }
;       asm volatile("" ::: "memory");
	ds_read_b128 v[154:157], v163 offset:49152
	ds_read_b128 v[164:167], v163 offset:50176
	ds_read_b128 v[168:171], v163 offset:51200
	ds_read_b128 v[172:175], v163 offset:52224
	ds_read_b128 v[176:179], v163 offset:53248
	ds_read_b128 v[180:183], v163 offset:54272
	ds_read_b128 v[184:187], v163 offset:55296
	ds_read_b128 v[188:191], v163 offset:56320
	global_load_lds_dwordx4 v[158:159], off
	v_lshl_add_u64 v[158:159], s[74:75], 0, v[150:151]
	s_mov_b32 m0, s94
	s_nop 0
	global_load_lds_dwordx4 v[158:159], off
	s_barrier
	s_waitcnt lgkmcnt(0)
	v_mfma_f32_16x16x32_bf16 v[60:63], v[128:131], v[154:157], v[60:63]
	v_mfma_f32_16x16x32_bf16 v[56:59], v[136:139], v[154:157], v[56:59]
	v_mfma_f32_16x16x32_bf16 v[44:47], v[128:131], v[168:171], v[44:47]
	v_mfma_f32_16x16x32_bf16 v[40:43], v[136:139], v[168:171], v[40:43]
	v_mfma_f32_16x16x32_bf16 v[28:31], v[128:131], v[176:179], v[28:31]
	v_mfma_f32_16x16x32_bf16 v[24:27], v[136:139], v[176:179], v[24:27]
	v_mfma_f32_16x16x32_bf16 v[20:23], v[128:131], v[184:187], v[20:23]
	v_mfma_f32_16x16x32_bf16 v[12:15], v[136:139], v[184:187], v[12:15]
	v_mfma_f32_16x16x32_bf16 v[60:63], v[132:135], v[164:167], v[60:63]
	v_mfma_f32_16x16x32_bf16 v[56:59], v[140:143], v[164:167], v[56:59]
	v_mfma_f32_16x16x32_bf16 v[44:47], v[132:135], v[172:175], v[44:47]
	v_mfma_f32_16x16x32_bf16 v[40:43], v[140:143], v[172:175], v[40:43]
	v_mfma_f32_16x16x32_bf16 v[28:31], v[132:135], v[180:183], v[28:31]
	v_mfma_f32_16x16x32_bf16 v[24:27], v[140:143], v[180:183], v[24:27]
	v_mfma_f32_16x16x32_bf16 v[20:23], v[132:135], v[188:191], v[20:23]
	v_mfma_f32_16x16x32_bf16 v[12:15], v[140:143], v[188:191], v[12:15]
	s_barrier
	s_add_u32 s0, s72, 0x80000
	s_addc_u32 s1, s73, 0
	s_add_i32 s2, s54, s14
	v_lshl_add_u64 v[128:129], s[0:1], 0, v[146:147]
	s_mov_b32 m0, s2
	s_nop 0
	global_load_lds_dwordx4 v[128:129], off
	v_lshl_add_u64 v[128:129], s[0:1], 0, v[152:153]
	s_add_i32 m0, s2, 0x2000
	s_nop 0
	global_load_lds_dwordx4 v[128:129], off
	s_waitcnt vmcnt(6)
	s_barrier
	v_mfma_f32_16x16x32_bf16 v[52:55], v[192:195], v[154:157], v[52:55]
	v_mfma_f32_16x16x32_bf16 v[48:51], v[200:203], v[154:157], v[48:51]
	v_mfma_f32_16x16x32_bf16 v[36:39], v[192:195], v[168:171], v[36:39]
	v_mfma_f32_16x16x32_bf16 v[32:35], v[200:203], v[168:171], v[32:35]
	v_mfma_f32_16x16x32_bf16 v[16:19], v[192:195], v[176:179], v[16:19]
	v_mfma_f32_16x16x32_bf16 v[8:11], v[200:203], v[176:179], v[8:11]
	v_mfma_f32_16x16x32_bf16 v[4:7], v[192:195], v[184:187], v[4:7]
	v_mfma_f32_16x16x32_bf16 v[0:3], v[200:203], v[184:187], v[0:3]
	v_mfma_f32_16x16x32_bf16 v[52:55], v[196:199], v[164:167], v[52:55]
	v_mfma_f32_16x16x32_bf16 v[48:51], v[204:207], v[164:167], v[48:51]
	v_mfma_f32_16x16x32_bf16 v[36:39], v[196:199], v[172:175], v[36:39]
	v_mfma_f32_16x16x32_bf16 v[32:35], v[204:207], v[172:175], v[32:35]
	v_mfma_f32_16x16x32_bf16 v[16:19], v[196:199], v[180:183], v[16:19]
	v_mfma_f32_16x16x32_bf16 v[8:11], v[204:207], v[180:183], v[8:11]
	v_mfma_f32_16x16x32_bf16 v[4:7], v[196:199], v[188:191], v[4:7]
	v_mfma_f32_16x16x32_bf16 v[0:3], v[204:207], v[188:191], v[0:3]
	s_add_i32 s7, s7, 2
	s_addk_i32 s57, 0x100
	s_addk_i32 s44, 0x100
	s_cmp_gt_u32 s7, 29
	s_barrier
	s_cbranch_scc0 .LBB0_42
	s_lshl_b32 s0, s66, 8
	v_mov_b32_e32 v128, v161
	v_mov_b32_e32 v129, v160
	s_add_i32 s0, s0, s67
	s_and_b64 vcc, exec, s[18:19]
	v_add_u32_e32 v156, s0, v129
	s_lshl_b32 s0, s46, 8
	s_or_b32 s0, s0, s83
	v_lshl_add_u32 v128, v128, 3, s0
	v_ashrrev_i32_e32 v157, 31, v156
	v_ashrrev_i32_e32 v129, 31, v128
	v_lshlrev_b64 v[212:213], 13, v[156:157]
	v_lshl_add_u64 v[130:131], s[8:9], 0, v[212:213]
	v_lshlrev_b64 v[154:155], 2, v[128:129]
	v_lshl_add_u64 v[128:129], v[130:131], 0, v[154:155]
	global_load_dwordx4 v[164:167], v[128:129], off offset:16
	global_load_dwordx4 v[168:171], v[128:129], off
	global_load_dwordx4 v[172:175], v[128:129], off offset:528
	global_load_dwordx4 v[176:179], v[128:129], off offset:512
	v_add_u32_e32 v128, 16, v156
	v_ashrrev_i32_e32 v129, 31, v128
	v_lshlrev_b64 v[214:215], 13, v[128:129]
	v_lshl_add_u64 v[128:129], s[8:9], 0, v[214:215]
	v_lshl_add_u64 v[128:129], v[128:129], 0, v[154:155]
	global_load_dwordx4 v[180:183], v[128:129], off offset:16
	global_load_dwordx4 v[184:187], v[128:129], off
	global_load_dwordx4 v[188:191], v[128:129], off offset:528
	global_load_dwordx4 v[192:195], v[128:129], off offset:512
	v_add_u32_e32 v128, 32, v156
	v_ashrrev_i32_e32 v129, 31, v128
	v_lshlrev_b64 v[216:217], 13, v[128:129]
	v_lshl_add_u64 v[128:129], s[8:9], 0, v[216:217]
	v_lshl_add_u64 v[128:129], v[128:129], 0, v[154:155]
	global_load_dwordx4 v[196:199], v[128:129], off offset:16
	global_load_dwordx4 v[200:203], v[128:129], off
	global_load_dwordx4 v[204:207], v[128:129], off offset:528
	global_load_dwordx4 v[208:211], v[128:129], off offset:512
	v_add_u32_e32 v128, 48, v156
	v_ashrrev_i32_e32 v129, 31, v128
	v_lshlrev_b64 v[158:159], 13, v[128:129]
	v_lshl_add_u64 v[128:129], s[8:9], 0, v[158:159]
	v_lshl_add_u64 v[136:137], v[128:129], 0, v[154:155]
	global_load_dwordx4 v[132:135], v[136:137], off offset:16
	global_load_dwordx4 v[140:143], v[136:137], off
	global_load_dwordx4 v[128:131], v[136:137], off offset:528
	s_nop 0
	global_load_dwordx4 v[136:139], v[136:137], off offset:512
	v_lshl_add_u64 v[212:213], s[16:17], 0, v[212:213]
	s_mov_b32 s46, s22
	s_mov_b32 s66, s20
	s_mov_b64 s[68:69], s[64:65]
	s_mov_b64 s[70:71], s[62:63]
	s_movk_i32 s54, 0x4000
	s_movk_i32 s55, 0x6000
	v_readlane_b32 s0, v255, 23
	s_cmpk_gt_u32 s0, 0xff
	s_cbranch_scc1 .Lds_out_x
	s_barrier

; #define G_STAGE(bufoff, gbase, voff) do { _Pragma("unroll") for (int _i = 0; _i < 2; ++_i) \
;         __builtin_amdgcn_global_load_lds((const unsigned*)((const char*)(gbase) + (voff)[_i]), (LAS unsigned*)(lds + (bufoff) + ldsw + _i * 8192), 16, 0, 0); } while (0)
; #define G_LDA(dst, b, h) do { _Pragma("unroll") for (int m = 0; m < 4; ++m) _Pragma("unroll") for (int k = 0; k < 2; ++k) dst[m][k] = *(const LAS bf16x8*)(lds + G_SA(b, h) + aoff + m * 2048 + k * 1024); } while (0)
; #define G_LDB(dst, b, h) do { _Pragma("unroll") for (int n = 0; n < 2; ++n) _Pragma("unroll") for (int k = 0; k < 2; ++k) dst[n][k] = *(const LAS bf16x8*)(lds + G_SB(b, h) + boff + n * 2048 + k * 1024); } while (0)
; #define G_MMA(ai, bj, At, Bt) do { __builtin_amdgcn_s_setprio(1); _Pragma("unroll") for (int m = 0; m < 4; ++m) _Pragma("unroll") for (int n = 0; n < 2; ++n) _Pragma("unroll") for (int k = 0; k < 2; ++k) \
;         acc[ai][bj][m][n] = __builtin_amdgcn_mfma_f32_16x16x32_bf16(Bt[n][k], At[m][k], acc[ai][bj][m][n], 0, 0, 0); __builtin_amdgcn_s_setprio(0); } while (0)
; #define G_WAIT_L(n) asm volatile("s_waitcnt lgkmcnt(" #n ")" ::: "memory")
; #define G_BAR __builtin_amdgcn_s_barrier()
; #define G_SCHED __builtin_amdgcn_sched_barrier(0)
;   DI const char* aptr(const Unit& u) const { return (const char*)(h + (size_t)u.pm * 256 * DM); }
; template <class J>
; DI void gemm_phase(LAS unsigned char* lds, const J& job) {
;     ...
;     const bool has_next = job.next(ui + 1, nxt);
;     const char* nA = has_next ? job.aptr(nxt) : cA; const char* nB = has_next ? job.bptr(nxt) : cB;
;     for (int t = 0; t < nt; t += 2) {
;       const bool last = (t == nt - 2);
;       const char* a1 = cA + G_KT(t + 1);
;       const char* a2 = last ? nA + G_KT(0) : cA + G_KT(t + 2); const char* b2 = last ? nB + G_KT(0) : cB + G_KT(t + 2);
;       const char* a3 = last ? nA + G_KT(1) : cA + G_KT(t + 3); const char* b3 = last ? nB + G_KT(1) : cB + G_KT(t + 3);
;       G_LDB(B0, 0, 0); G_SCHED; G_LDA(At, 0, 0); G_STAGE(G_SA(1, 1), a1 + hstepA, voffA);
;       G_WAIT_L(8); G_BAR; G_WAIT_L(0); G_MMA(0, 0, At, B0); G_BAR; G_SCHED;
;       G_LDB(B1, 0, 1); G_STAGE(G_SB(0, 0), b2, voffB);
;       G_BAR; G_WAIT_L(0); G_MMA(0, 1, At, B1); G_BAR;
;       G_LDA(At, 0, 1); G_STAGE(G_SA(0, 0), a2, voffA);
;       G_BAR; G_WAIT_L(0); G_MMA(1, 0, At, B0); G_BAR; G_SCHED;
.LBB0_74:
	s_add_i32 s1, s56, 0xffffff80
	s_and_b32 s0, s7, 0xf80
	s_and_b32 s1, s1, 0xf00
	s_add_u32 s57, s68, s1
	s_addc_u32 s70, s69, 0
	s_add_u32 s1, s66, s1
	s_addc_u32 s71, s67, 0
	s_and_b32 s72, s56, 0xf80
	s_add_u32 s80, s68, s72
	s_addc_u32 s73, s69, 0
	s_add_u32 s38, s66, s72
	s_addc_u32 s2, s67, 0
	s_cmp_eq_u32 s6, 28
	s_cselect_b32 s75, s46, s70
	s_cselect_b32 s74, s45, s57
	s_cselect_b32 s77, vcc_lo, s71
	s_cselect_b32 s76, s47, s1
	s_cselect_b32 s73, s97, s73
	s_cselect_b32 s72, s33, s80
	s_cselect_b32 s71, s5, s2
	s_cselect_b32 s70, vcc_hi, s38
	s_add_i32 s2, s84, 0x100
	v_add_u32_e32 v100, s2, v248
	ds_read_b128 v[84:87], v100
	ds_read_b128 v[88:91], v100 offset:1024
	ds_read_b128 v[96:99], v100 offset:2048
	ds_read_b128 v[100:103], v100 offset:3072
	s_add_u32 s0, s19, s0
	s_addc_u32 s1, s21, 0
	v_lshl_add_u64 v[186:187], s[0:1], 0, v[148:149]
	s_add_i32 m0, s14, 0xc000
	ds_read_b128 v[154:157], v249
	ds_read_b128 v[158:161], v249 offset:1024
	ds_read_b128 v[162:165], v249 offset:2048
	ds_read_b128 v[166:169], v249 offset:3072
	ds_read_b128 v[170:173], v249 offset:4096
	ds_read_b128 v[174:177], v249 offset:5120
	ds_read_b128 v[178:181], v249 offset:6144
	ds_read_b128 v[182:185], v249 offset:7168
	global_load_lds_dwordx4 v[186:187], off
	v_lshl_add_u64 v[186:187], s[0:1], 0, v[150:151]
	s_add_i32 m0, s14, 0xe000
	s_nop 0
	global_load_lds_dwordx4 v[186:187], off
	s_waitcnt lgkmcnt(8)
	s_barrier
	s_waitcnt lgkmcnt(0)
	v_mfma_f32_16x16x32_bf16 v[140:143], v[84:87], v[154:157], v[140:143]
	v_mfma_f32_16x16x32_bf16 v[136:139], v[96:99], v[154:157], v[136:139]
	v_mfma_f32_16x16x32_bf16 v[124:127], v[84:87], v[162:165], v[124:127]
	v_mfma_f32_16x16x32_bf16 v[120:123], v[96:99], v[162:165], v[120:123]
	v_mfma_f32_16x16x32_bf16 v[108:111], v[84:87], v[170:173], v[108:111]
	v_mfma_f32_16x16x32_bf16 v[104:107], v[96:99], v[170:173], v[104:107]
	v_mfma_f32_16x16x32_bf16 v[76:79], v[84:87], v[178:181], v[76:79]
	v_mfma_f32_16x16x32_bf16 v[72:75], v[96:99], v[178:181], v[72:75]
	v_mfma_f32_16x16x32_bf16 v[140:143], v[88:91], v[158:161], v[140:143]
	v_mfma_f32_16x16x32_bf16 v[136:139], v[100:103], v[158:161], v[136:139]
	v_mfma_f32_16x16x32_bf16 v[124:127], v[88:91], v[166:169], v[124:127]
	v_mfma_f32_16x16x32_bf16 v[120:123], v[100:103], v[166:169], v[120:123]
	v_mfma_f32_16x16x32_bf16 v[108:111], v[88:91], v[174:177], v[108:111]
	v_mfma_f32_16x16x32_bf16 v[104:107], v[100:103], v[174:177], v[104:107]
	v_mfma_f32_16x16x32_bf16 v[76:79], v[88:91], v[182:185], v[76:79]
	v_mfma_f32_16x16x32_bf16 v[72:75], v[100:103], v[182:185], v[72:75]
	s_barrier
	s_add_i32 s38, s85, 0x100
	s_add_i32 s0, s2, s78
	v_add_u32_e32 v198, s38, v248
	v_lshl_add_u64 v[202:203], s[76:77], 0, v[146:147]
	s_mov_b32 m0, s0
	ds_read_b128 v[186:189], v198
	ds_read_b128 v[190:193], v198 offset:1024
	ds_read_b128 v[194:197], v198 offset:2048
	ds_read_b128 v[198:201], v198 offset:3072
	global_load_lds_dwordx4 v[202:203], off
	v_lshl_add_u64 v[202:203], s[76:77], 0, v[152:153]
	s_add_i32 m0, s0, 0x2000
	s_nop 0
	global_load_lds_dwordx4 v[202:203], off
	s_barrier
	s_waitcnt lgkmcnt(0)
	v_mfma_f32_16x16x32_bf16 v[132:135], v[186:189], v[154:157], v[132:135]
	v_mfma_f32_16x16x32_bf16 v[128:131], v[194:197], v[154:157], v[128:131]
	v_mfma_f32_16x16x32_bf16 v[116:119], v[186:189], v[162:165], v[116:119]
	v_mfma_f32_16x16x32_bf16 v[112:115], v[194:197], v[162:165], v[112:115]
	v_mfma_f32_16x16x32_bf16 v[92:95], v[186:189], v[170:173], v[92:95]
	v_mfma_f32_16x16x32_bf16 v[80:83], v[194:197], v[170:173], v[80:83]
	v_mfma_f32_16x16x32_bf16 v[68:71], v[186:189], v[178:181], v[68:71]
	v_mfma_f32_16x16x32_bf16 v[64:67], v[194:197], v[178:181], v[64:67]
	v_mfma_f32_16x16x32_bf16 v[132:135], v[190:193], v[158:161], v[132:135]
	v_mfma_f32_16x16x32_bf16 v[128:131], v[198:201], v[158:161], v[128:131]
	v_mfma_f32_16x16x32_bf16 v[116:119], v[190:193], v[166:169], v[116:119]
	v_mfma_f32_16x16x32_bf16 v[112:115], v[198:201], v[166:169], v[112:115]
	v_mfma_f32_16x16x32_bf16 v[92:95], v[190:193], v[174:177], v[92:95]
	v_mfma_f32_16x16x32_bf16 v[80:83], v[198:201], v[174:177], v[80:83]
	v_mfma_f32_16x16x32_bf16 v[68:71], v[190:193], v[182:185], v[68:71]
	v_mfma_f32_16x16x32_bf16 v[64:67], v[198:201], v[182:185], v[64:67]
	s_mov_b32 m0, s14
	v_lshl_add_u64 v[202:203], s[74:75], 0, v[148:149]
	s_barrier
	ds_read_b128 v[154:157], v249 offset:16384
	ds_read_b128 v[158:161], v249 offset:17408
	ds_read_b128 v[162:165], v249 offset:18432
	ds_read_b128 v[166:169], v249 offset:19456
	ds_read_b128 v[170:173], v249 offset:20480
	ds_read_b128 v[174:177], v249 offset:21504
	ds_read_b128 v[178:181], v249 offset:22528
	ds_read_b128 v[182:185], v249 offset:23552
	global_load_lds_dwordx4 v[202:203], off
	v_lshl_add_u64 v[202:203], s[74:75], 0, v[150:151]
	s_mov_b32 m0, s15
	s_nop 0
	global_load_lds_dwordx4 v[202:203], off
	s_barrier
	s_waitcnt lgkmcnt(0)
	v_mfma_f32_16x16x32_bf16 v[60:63], v[84:87], v[154:157], v[60:63]
	v_mfma_f32_16x16x32_bf16 v[56:59], v[96:99], v[154:157], v[56:59]
	v_mfma_f32_16x16x32_bf16 v[44:47], v[84:87], v[162:165], v[44:47]
	v_mfma_f32_16x16x32_bf16 v[40:43], v[96:99], v[162:165], v[40:43]
	v_mfma_f32_16x16x32_bf16 v[28:31], v[84:87], v[170:173], v[28:31]
	v_mfma_f32_16x16x32_bf16 v[24:27], v[96:99], v[170:173], v[24:27]
	v_mfma_f32_16x16x32_bf16 v[12:15], v[84:87], v[178:181], v[12:15]
	v_mfma_f32_16x16x32_bf16 v[8:11], v[96:99], v[178:181], v[8:11]
	v_mfma_f32_16x16x32_bf16 v[60:63], v[88:91], v[158:161], v[60:63]
	v_mfma_f32_16x16x32_bf16 v[56:59], v[100:103], v[158:161], v[56:59]
	v_mfma_f32_16x16x32_bf16 v[44:47], v[88:91], v[166:169], v[44:47]
	v_mfma_f32_16x16x32_bf16 v[40:43], v[100:103], v[166:169], v[40:43]
	v_mfma_f32_16x16x32_bf16 v[28:31], v[88:91], v[174:177], v[28:31]
	v_mfma_f32_16x16x32_bf16 v[24:27], v[100:103], v[174:177], v[24:27]
	v_mfma_f32_16x16x32_bf16 v[12:15], v[88:91], v[182:185], v[12:15]
	v_mfma_f32_16x16x32_bf16 v[8:11], v[100:103], v[182:185], v[8:11]
	s_barrier
; #define G_STAGE(bufoff, gbase, voff) do { _Pragma("unroll") for (int _i = 0; _i < 2; ++_i) \
;         __builtin_amdgcn_global_load_lds((const unsigned*)((const char*)(gbase) + (voff)[_i]), (LAS unsigned*)(lds + (bufoff) + ldsw + _i * 8192), 16, 0, 0); } while (0)
; #define G_LDA(dst, b, h) do { _Pragma("unroll") for (int m = 0; m < 4; ++m) _Pragma("unroll") for (int k = 0; k < 2; ++k) dst[m][k] = *(const LAS bf16x8*)(lds + G_SA(b, h) + aoff + m * 2048 + k * 1024); } while (0)
; #define G_LDB(dst, b, h) do { _Pragma("unroll") for (int n = 0; n < 2; ++n) _Pragma("unroll") for (int k = 0; k < 2; ++k) dst[n][k] = *(const LAS bf16x8*)(lds + G_SB(b, h) + boff + n * 2048 + k * 1024); } while (0)
; #define G_MMA(ai, bj, At, Bt) do { __builtin_amdgcn_s_setprio(1); _Pragma("unroll") for (int m = 0; m < 4; ++m) _Pragma("unroll") for (int n = 0; n < 2; ++n) _Pragma("unroll") for (int k = 0; k < 2; ++k) \
;         acc[ai][bj][m][n] = __builtin_amdgcn_mfma_f32_16x16x32_bf16(Bt[n][k], At[m][k], acc[ai][bj][m][n], 0, 0, 0); __builtin_amdgcn_s_setprio(0); } while (0)
; #define G_WAIT_V(n) asm volatile("s_waitcnt vmcnt(" #n ")" ::: "memory")
; #define G_WAIT_L(n) asm volatile("s_waitcnt lgkmcnt(" #n ")" ::: "memory")
; #define G_BAR __builtin_amdgcn_s_barrier()
; #define G_SCHED __builtin_amdgcn_sched_barrier(0)
; template <class J>
; DI void gemm_phase(LAS unsigned char* lds, const J& job) {
;     ...
;       G_STAGE(G_SB(0, 1), b2 + hstepB, voffB);
;       G_WAIT_V(6); G_BAR; G_MMA(1, 1, At, B1); G_BAR;
;       G_LDB(B0, 1, 0); G_SCHED; G_LDA(At, 1, 0); G_STAGE(G_SA(0, 1), a2 + hstepA, voffA);
;       G_WAIT_L(8); G_BAR; G_WAIT_L(0); G_MMA(0, 0, At, B0); G_BAR; G_SCHED;
;       G_LDB(B1, 1, 1); G_STAGE(G_SB(1, 0), b3, voffB);
;       G_BAR; G_WAIT_L(0); G_MMA(0, 1, At, B1); G_BAR;
;       G_LDA(At, 1, 1); G_STAGE(G_SA(1, 0), a3, voffA);
	s_add_u32 s0, s76, 0x1000000
	s_addc_u32 s1, s77, 0
	s_add_i32 s2, s38, s78
	v_lshl_add_u64 v[84:85], s[0:1], 0, v[146:147]
	s_mov_b32 m0, s2
	s_nop 0
	global_load_lds_dwordx4 v[84:85], off
	v_lshl_add_u64 v[84:85], s[0:1], 0, v[152:153]
	s_add_i32 m0, s2, 0x2000
	s_nop 0
	global_load_lds_dwordx4 v[84:85], off
	s_waitcnt vmcnt(6)
	s_barrier
	v_mfma_f32_16x16x32_bf16 v[52:55], v[186:189], v[154:157], v[52:55]
	v_mfma_f32_16x16x32_bf16 v[48:51], v[194:197], v[154:157], v[48:51]
	v_mfma_f32_16x16x32_bf16 v[36:39], v[186:189], v[162:165], v[36:39]
	v_mfma_f32_16x16x32_bf16 v[32:35], v[194:197], v[162:165], v[32:35]
	v_mfma_f32_16x16x32_bf16 v[20:23], v[186:189], v[170:173], v[20:23]
	v_mfma_f32_16x16x32_bf16 v[16:19], v[194:197], v[170:173], v[16:19]
	v_mfma_f32_16x16x32_bf16 v[4:7], v[186:189], v[178:181], v[4:7]
	v_mfma_f32_16x16x32_bf16 v[0:3], v[194:197], v[178:181], v[0:3]
	v_mfma_f32_16x16x32_bf16 v[52:55], v[190:193], v[158:161], v[52:55]
	v_mfma_f32_16x16x32_bf16 v[48:51], v[198:201], v[158:161], v[48:51]
	v_mfma_f32_16x16x32_bf16 v[36:39], v[190:193], v[166:169], v[36:39]
	v_mfma_f32_16x16x32_bf16 v[32:35], v[198:201], v[166:169], v[32:35]
	v_mfma_f32_16x16x32_bf16 v[20:23], v[190:193], v[174:177], v[20:23]
	v_mfma_f32_16x16x32_bf16 v[16:19], v[198:201], v[174:177], v[16:19]
	v_mfma_f32_16x16x32_bf16 v[4:7], v[190:193], v[182:185], v[4:7]
	v_mfma_f32_16x16x32_bf16 v[0:3], v[198:201], v[182:185], v[0:3]
	s_add_i32 s2, s88, 0x100
	v_add_u32_e32 v100, s2, v248
	s_barrier
	ds_read_b128 v[84:87], v100
	ds_read_b128 v[88:91], v100 offset:1024
	ds_read_b128 v[96:99], v100 offset:2048
	ds_read_b128 v[100:103], v100 offset:3072
	s_add_u32 s0, s74, 0x80000
	s_addc_u32 s1, s75, 0
	s_mov_b32 m0, s83
	v_lshl_add_u64 v[186:187], s[0:1], 0, v[148:149]
	ds_read_b128 v[154:157], v249 offset:32768
	ds_read_b128 v[158:161], v249 offset:33792
	ds_read_b128 v[162:165], v249 offset:34816
	ds_read_b128 v[166:169], v249 offset:35840
	ds_read_b128 v[170:173], v249 offset:36864
	ds_read_b128 v[174:177], v249 offset:37888
	ds_read_b128 v[178:181], v249 offset:38912
	ds_read_b128 v[182:185], v249 offset:39936
	global_load_lds_dwordx4 v[186:187], off
	v_lshl_add_u64 v[186:187], s[0:1], 0, v[150:151]
	s_mov_b32 m0, s36
	s_nop 0
	global_load_lds_dwordx4 v[186:187], off
	s_waitcnt lgkmcnt(8)
	s_barrier
	s_waitcnt lgkmcnt(0)
	v_mfma_f32_16x16x32_bf16 v[140:143], v[84:87], v[154:157], v[140:143]
	v_mfma_f32_16x16x32_bf16 v[136:139], v[96:99], v[154:157], v[136:139]
	v_mfma_f32_16x16x32_bf16 v[124:127], v[84:87], v[162:165], v[124:127]
	v_mfma_f32_16x16x32_bf16 v[120:123], v[96:99], v[162:165], v[120:123]
	v_mfma_f32_16x16x32_bf16 v[108:111], v[84:87], v[170:173], v[108:111]
	v_mfma_f32_16x16x32_bf16 v[104:107], v[96:99], v[170:173], v[104:107]
	v_mfma_f32_16x16x32_bf16 v[76:79], v[84:87], v[178:181], v[76:79]
	v_mfma_f32_16x16x32_bf16 v[72:75], v[96:99], v[178:181], v[72:75]
	v_mfma_f32_16x16x32_bf16 v[140:143], v[88:91], v[158:161], v[140:143]
	v_mfma_f32_16x16x32_bf16 v[136:139], v[100:103], v[158:161], v[136:139]
	v_mfma_f32_16x16x32_bf16 v[124:127], v[88:91], v[166:169], v[124:127]
	v_mfma_f32_16x16x32_bf16 v[120:123], v[100:103], v[166:169], v[120:123]
	v_mfma_f32_16x16x32_bf16 v[108:111], v[88:91], v[174:177], v[108:111]
	v_mfma_f32_16x16x32_bf16 v[104:107], v[100:103], v[174:177], v[104:107]
	v_mfma_f32_16x16x32_bf16 v[76:79], v[88:91], v[182:185], v[76:79]
	v_mfma_f32_16x16x32_bf16 v[72:75], v[100:103], v[182:185], v[72:75]
	s_barrier
	s_add_i32 s38, s89, 0x100
	s_add_i32 s0, s2, s78
	v_add_u32_e32 v198, s38, v248
	v_lshl_add_u64 v[202:203], s[70:71], 0, v[146:147]
	s_mov_b32 m0, s0
	ds_read_b128 v[186:189], v198
	ds_read_b128 v[190:193], v198 offset:1024
	ds_read_b128 v[194:197], v198 offset:2048
	ds_read_b128 v[198:201], v198 offset:3072
	global_load_lds_dwordx4 v[202:203], off
	v_lshl_add_u64 v[202:203], s[70:71], 0, v[152:153]
	s_add_i32 m0, s0, 0x2000
	s_nop 0
	global_load_lds_dwordx4 v[202:203], off
	s_barrier
	s_waitcnt lgkmcnt(0)
	v_mfma_f32_16x16x32_bf16 v[132:135], v[186:189], v[154:157], v[132:135]
	v_mfma_f32_16x16x32_bf16 v[128:131], v[194:197], v[154:157], v[128:131]
	v_mfma_f32_16x16x32_bf16 v[116:119], v[186:189], v[162:165], v[116:119]
	v_mfma_f32_16x16x32_bf16 v[112:115], v[194:197], v[162:165], v[112:115]
	v_mfma_f32_16x16x32_bf16 v[92:95], v[186:189], v[170:173], v[92:95]
	v_mfma_f32_16x16x32_bf16 v[80:83], v[194:197], v[170:173], v[80:83]
	v_mfma_f32_16x16x32_bf16 v[68:71], v[186:189], v[178:181], v[68:71]
	v_mfma_f32_16x16x32_bf16 v[64:67], v[194:197], v[178:181], v[64:67]
	v_mfma_f32_16x16x32_bf16 v[132:135], v[190:193], v[158:161], v[132:135]
	v_mfma_f32_16x16x32_bf16 v[128:131], v[198:201], v[158:161], v[128:131]
	v_mfma_f32_16x16x32_bf16 v[116:119], v[190:193], v[166:169], v[116:119]
	v_mfma_f32_16x16x32_bf16 v[112:115], v[198:201], v[166:169], v[112:115]
	v_mfma_f32_16x16x32_bf16 v[92:95], v[190:193], v[174:177], v[92:95]
	v_mfma_f32_16x16x32_bf16 v[80:83], v[198:201], v[174:177], v[80:83]
	v_mfma_f32_16x16x32_bf16 v[68:71], v[190:193], v[182:185], v[68:71]
	v_mfma_f32_16x16x32_bf16 v[64:67], v[198:201], v[182:185], v[64:67]
	s_mov_b32 m0, s24
	v_lshl_add_u64 v[202:203], s[72:73], 0, v[148:149]
	s_barrier
	ds_read_b128 v[154:157], v249 offset:49152
	ds_read_b128 v[158:161], v249 offset:50176
	ds_read_b128 v[162:165], v249 offset:51200
	ds_read_b128 v[166:169], v249 offset:52224
	ds_read_b128 v[170:173], v249 offset:53248
	ds_read_b128 v[174:177], v249 offset:54272
	ds_read_b128 v[178:181], v249 offset:55296
	ds_read_b128 v[182:185], v249 offset:56320
	global_load_lds_dwordx4 v[202:203], off
	v_lshl_add_u64 v[202:203], s[72:73], 0, v[150:151]
	s_mov_b32 m0, s25
	s_nop 0
	global_load_lds_dwordx4 v[202:203], off
	s_barrier
; #define G_STAGE(bufoff, gbase, voff) do { _Pragma("unroll") for (int _i = 0; _i < 2; ++_i) \
;         __builtin_amdgcn_global_load_lds((const unsigned*)((const char*)(gbase) + (voff)[_i]), (LAS unsigned*)(lds + (bufoff) + ldsw + _i * 8192), 16, 0, 0); } while (0)
; #define G_MMA(ai, bj, At, Bt) do { __builtin_amdgcn_s_setprio(1); _Pragma("unroll") for (int m = 0; m < 4; ++m) _Pragma("unroll") for (int n = 0; n < 2; ++n) _Pragma("unroll") for (int k = 0; k < 2; ++k) \
;         acc[ai][bj][m][n] = __builtin_amdgcn_mfma_f32_16x16x32_bf16(Bt[n][k], At[m][k], acc[ai][bj][m][n], 0, 0, 0); __builtin_amdgcn_s_setprio(0); } while (0)
; #define G_WAIT_V(n) asm volatile("s_waitcnt vmcnt(" #n ")" ::: "memory")
; #define G_WAIT_L(n) asm volatile("s_waitcnt lgkmcnt(" #n ")" ::: "memory")
; #define G_BAR __builtin_amdgcn_s_barrier()
; #define G_SCHED __builtin_amdgcn_sched_barrier(0)
; template <class J>
; DI void gemm_phase(LAS unsigned char* lds, const J& job) {
;     ...
;       G_BAR; G_WAIT_L(0); G_MMA(1, 0, At, B0); G_BAR; G_SCHED;
;       G_STAGE(G_SB(1, 1), b3 + hstepB, voffB);
;       G_WAIT_V(6); G_BAR; G_MMA(1, 1, At, B1); G_BAR;
;     }
	s_waitcnt lgkmcnt(0)
	v_mfma_f32_16x16x32_bf16 v[60:63], v[84:87], v[154:157], v[60:63]
	v_mfma_f32_16x16x32_bf16 v[56:59], v[96:99], v[154:157], v[56:59]
	v_mfma_f32_16x16x32_bf16 v[44:47], v[84:87], v[162:165], v[44:47]
	v_mfma_f32_16x16x32_bf16 v[40:43], v[96:99], v[162:165], v[40:43]
	v_mfma_f32_16x16x32_bf16 v[28:31], v[84:87], v[170:173], v[28:31]
	v_mfma_f32_16x16x32_bf16 v[24:27], v[96:99], v[170:173], v[24:27]
	v_mfma_f32_16x16x32_bf16 v[12:15], v[84:87], v[178:181], v[12:15]
	v_mfma_f32_16x16x32_bf16 v[8:11], v[96:99], v[178:181], v[8:11]
	v_mfma_f32_16x16x32_bf16 v[60:63], v[88:91], v[158:161], v[60:63]
	v_mfma_f32_16x16x32_bf16 v[56:59], v[100:103], v[158:161], v[56:59]
	v_mfma_f32_16x16x32_bf16 v[44:47], v[88:91], v[166:169], v[44:47]
	v_mfma_f32_16x16x32_bf16 v[40:43], v[100:103], v[166:169], v[40:43]
	v_mfma_f32_16x16x32_bf16 v[28:31], v[88:91], v[174:177], v[28:31]
	v_mfma_f32_16x16x32_bf16 v[24:27], v[100:103], v[174:177], v[24:27]
	v_mfma_f32_16x16x32_bf16 v[12:15], v[88:91], v[182:185], v[12:15]
	v_mfma_f32_16x16x32_bf16 v[8:11], v[100:103], v[182:185], v[8:11]
	s_barrier
	s_add_u32 s0, s70, 0x1000000
	s_addc_u32 s1, s71, 0
	s_add_i32 s2, s38, s78
	v_lshl_add_u64 v[84:85], s[0:1], 0, v[146:147]
	s_mov_b32 m0, s2
	s_nop 0
	global_load_lds_dwordx4 v[84:85], off
	v_lshl_add_u64 v[84:85], s[0:1], 0, v[152:153]
	s_add_i32 m0, s2, 0x2000
	s_nop 0
	global_load_lds_dwordx4 v[84:85], off
	s_waitcnt vmcnt(6)
	s_barrier
	v_mfma_f32_16x16x32_bf16 v[52:55], v[186:189], v[154:157], v[52:55]
	v_mfma_f32_16x16x32_bf16 v[48:51], v[194:197], v[154:157], v[48:51]
	v_mfma_f32_16x16x32_bf16 v[36:39], v[186:189], v[162:165], v[36:39]
	v_mfma_f32_16x16x32_bf16 v[32:35], v[194:197], v[162:165], v[32:35]
	v_mfma_f32_16x16x32_bf16 v[20:23], v[186:189], v[170:173], v[20:23]
	v_mfma_f32_16x16x32_bf16 v[16:19], v[194:197], v[170:173], v[16:19]
	v_mfma_f32_16x16x32_bf16 v[4:7], v[186:189], v[178:181], v[4:7]
	v_mfma_f32_16x16x32_bf16 v[0:3], v[194:197], v[178:181], v[0:3]
	v_mfma_f32_16x16x32_bf16 v[52:55], v[190:193], v[158:161], v[52:55]
	v_mfma_f32_16x16x32_bf16 v[48:51], v[198:201], v[158:161], v[48:51]
	v_mfma_f32_16x16x32_bf16 v[36:39], v[190:193], v[166:169], v[36:39]
	v_mfma_f32_16x16x32_bf16 v[32:35], v[198:201], v[166:169], v[32:35]
	v_mfma_f32_16x16x32_bf16 v[20:23], v[190:193], v[174:177], v[20:23]
	v_mfma_f32_16x16x32_bf16 v[16:19], v[198:201], v[174:177], v[16:19]
	v_mfma_f32_16x16x32_bf16 v[4:7], v[190:193], v[182:185], v[4:7]
	v_mfma_f32_16x16x32_bf16 v[0:3], v[198:201], v[182:185], v[0:3]
	s_add_i32 s6, s6, 2
	s_addk_i32 s56, 0x100
	s_addk_i32 s7, 0x100
	s_cmp_gt_u32 s6, 29
	s_barrier
	s_cbranch_scc0 .LBB0_74
;   DI void epi(const Acc& acc, const Unit& u, int wr, int wc, int fr, int fq) const {
;     const int cc = u.pn * 64 + 16 * wc + 4 * fq;
;     u32x2 zz[2][4][4];
; #pragma unroll
;     for (int ai = 0; ai < 2; ++ai)
; #pragma unroll
;       for (int m = 0; m < 4; ++m) {
;         const u16* zr = Z + (size_t)(u.pm * 256 + ai * HALF + wr * 64 + m * 16 + fr) * NGATE + cc;
; #pragma unroll
;         for (int br = 0; br < 4; ++br) zz[ai][m][br] = *(const u32x2*)(zr + br * 2048);
;       }
;     f32x4 bg[4];
; #pragma unroll
;     for (int br = 0; br < 4; ++br) bg[br] = *(const f32x4*)(bgate + br * 2048 + cc);
;     asm volatile("" ::: "memory");
	v_mov_b32_e32 v84, v247
	v_mov_b32_e32 v85, v246
	s_lshl_b32 s0, s44, 6
	s_or_b32 s0, s0, s96
	v_lshl_add_u32 v84, v84, 2, s0
	s_lshl_b32 s0, s64, 8
	s_add_i32 s0, s0, s37
	v_add_u32_e32 v224, s0, v85
	v_ashrrev_i32_e32 v85, 31, v84
	v_lshlrev_b64 v[154:155], 1, v[84:85]
	v_ashrrev_i32_e32 v225, 31, v224
	v_lshl_add_u64 v[86:87], s[26:27], 0, v[154:155]
	v_lshlrev_b64 v[88:89], 14, v[224:225]
	v_lshl_add_u64 v[88:89], v[86:87], 0, v[88:89]
	v_add_co_u32_e32 v90, vcc, s82, v88
	v_add_u32_e32 v212, 16, v224
	s_nop 0
	v_addc_co_u32_e32 v91, vcc, 0, v89, vcc
	v_ashrrev_i32_e32 v213, 31, v212
	v_add_co_u32_e32 v96, vcc, s92, v88
	v_lshlrev_b64 v[98:99], 14, v[212:213]
	s_nop 0
	v_addc_co_u32_e32 v97, vcc, 0, v89, vcc
	v_lshl_add_u64 v[98:99], v[86:87], 0, v[98:99]
	v_add_co_u32_e32 v100, vcc, s82, v98
	v_add_u32_e32 v202, 32, v224
	s_nop 0
	v_addc_co_u32_e32 v101, vcc, 0, v99, vcc
	global_load_dwordx2 v[230:231], v[90:91], off offset:-4096
	global_load_dwordx2 v[226:227], v[90:91], off
	global_load_dwordx2 v[220:221], v[100:101], off offset:-4096
	global_load_dwordx2 v[214:215], v[100:101], off
	v_add_co_u32_e32 v90, vcc, s92, v98
	v_ashrrev_i32_e32 v203, 31, v202
	s_nop 0
	v_addc_co_u32_e32 v91, vcc, 0, v99, vcc
	global_load_dwordx2 v[232:233], v[88:89], off
	global_load_dwordx2 v[228:229], v[96:97], off
	global_load_dwordx2 v[222:223], v[98:99], off
	global_load_dwordx2 v[216:217], v[90:91], off
	v_lshlrev_b64 v[88:89], 14, v[202:203]
	v_lshl_add_u64 v[88:89], v[86:87], 0, v[88:89]
	v_add_co_u32_e32 v90, vcc, s82, v88
	v_add_u32_e32 v190, 48, v224
	s_nop 0
	v_addc_co_u32_e32 v91, vcc, 0, v89, vcc
	v_ashrrev_i32_e32 v191, 31, v190
	v_add_co_u32_e32 v96, vcc, s92, v88
	v_lshlrev_b64 v[98:99], 14, v[190:191]
	s_nop 0
	v_addc_co_u32_e32 v97, vcc, 0, v89, vcc
	v_lshl_add_u64 v[98:99], v[86:87], 0, v[98:99]
	v_add_co_u32_e32 v100, vcc, s82, v98
	v_add_u32_e32 v184, 0x80, v224
	s_nop 0
	v_addc_co_u32_e32 v101, vcc, 0, v99, vcc
	global_load_dwordx2 v[210:211], v[90:91], off offset:-4096
	global_load_dwordx2 v[206:207], v[90:91], off
	global_load_dwordx2 v[200:201], v[100:101], off offset:-4096
	global_load_dwordx2 v[192:193], v[100:101], off
	v_add_co_u32_e32 v90, vcc, s92, v98
	v_lshl_add_u64 v[84:85], v[84:85], 2, s[12:13]
	v_ashrrev_i32_e32 v185, 31, v184
	v_addc_co_u32_e32 v91, vcc, 0, v99, vcc
	global_load_dwordx4 v[100:103], v[84:85], off
	global_load_dwordx2 v[218:219], v[88:89], off
	global_load_dwordx2 v[208:209], v[96:97], off
	global_load_dwordx2 v[204:205], v[98:99], off
	global_load_dwordx2 v[198:199], v[90:91], off
	v_lshlrev_b64 v[88:89], 14, v[184:185]
	v_lshl_add_u64 v[88:89], v[86:87], 0, v[88:89]
	v_add_co_u32_e32 v90, vcc, s82, v88
	v_add_u32_e32 v174, 0x90, v224
	s_nop 0
	v_addc_co_u32_e32 v91, vcc, 0, v89, vcc
	v_add_co_u32_e32 v156, vcc, s92, v88
	v_ashrrev_i32_e32 v175, 31, v174
	s_nop 0
	v_addc_co_u32_e32 v157, vcc, 0, v89, vcc
	v_add_co_u32_e32 v96, vcc, s82, v84
	v_lshlrev_b64 v[158:159], 14, v[174:175]
	s_nop 0
	v_addc_co_u32_e32 v97, vcc, 0, v85, vcc
	global_load_dwordx4 v[96:99], v[96:97], off
	v_lshl_add_u64 v[158:159], v[86:87], 0, v[158:159]
	v_add_co_u32_e32 v160, vcc, s82, v158
	v_add_u32_e32 v164, 0xa0, v224
	s_nop 0
	v_addc_co_u32_e32 v161, vcc, 0, v159, vcc
	global_load_dwordx2 v[194:195], v[90:91], off offset:-4096
	global_load_dwordx2 v[186:187], v[90:91], off
	global_load_dwordx2 v[180:181], v[160:161], off offset:-4096
	global_load_dwordx2 v[176:177], v[160:161], off
	v_add_co_u32_e32 v90, vcc, s92, v158
	v_ashrrev_i32_e32 v165, 31, v164
	s_nop 0
	v_addc_co_u32_e32 v91, vcc, 0, v159, vcc
	global_load_dwordx2 v[196:197], v[88:89], off
	global_load_dwordx2 v[188:189], v[156:157], off
	global_load_dwordx2 v[182:183], v[158:159], off
	global_load_dwordx2 v[178:179], v[90:91], off
	v_lshlrev_b64 v[88:89], 14, v[164:165]
	v_lshl_add_u64 v[162:163], v[86:87], 0, v[88:89]
	v_add_co_u32_e32 v158, vcc, s82, v162
	v_add_u32_e32 v156, 0xb0, v224
	s_nop 0
	v_addc_co_u32_e32 v159, vcc, 0, v163, vcc
	v_add_co_u32_e32 v168, vcc, s92, v162
	v_ashrrev_i32_e32 v157, 31, v156
	s_nop 0
	v_addc_co_u32_e32 v169, vcc, 0, v163, vcc
	v_add_co_u32_e32 v88, vcc, s54, v84
	v_lshlrev_b64 v[160:161], 14, v[156:157]
	s_nop 0
	v_addc_co_u32_e32 v89, vcc, 0, v85, vcc
	global_load_dwordx4 v[88:91], v[88:89], off
	v_lshl_add_u64 v[250:251], v[86:87], 0, v[160:161]
	v_add_co_u32_e32 v86, vcc, s82, v250
	s_mov_b32 s44, s20
	s_nop 0
	v_addc_co_u32_e32 v87, vcc, 0, v251, vcc
	v_add_co_u32_e32 v84, vcc, s55, v84
	global_load_dwordx2 v[170:171], v[158:159], off offset:-4096
	global_load_dwordx2 v[166:167], v[158:159], off
	global_load_dwordx2 v[160:161], v[86:87], off offset:-4096
	s_nop 0
	global_load_dwordx2 v[158:159], v[86:87], off
	v_addc_co_u32_e32 v85, vcc, 0, v85, vcc
	global_load_dwordx4 v[84:87], v[84:85], off
	v_add_co_u32_e32 v252, vcc, s92, v250
	s_mov_b32 s64, s18
	s_nop 0
	v_addc_co_u32_e32 v253, vcc, 0, v251, vcc
	s_and_b64 vcc, exec, s[8:9]
	s_mov_b64 s[66:67], s[62:63]
	s_mov_b64 s[68:69], s[22:23]
	v_readlane_b32 s0, v255, 23
	s_cmpk_gt_u32 s0, 0xff
	s_cbranch_scc1 .Lds_gate_x
	s_barrier

; #define G_STAGE(bufoff, gbase, voff) do { _Pragma("unroll") for (int _i = 0; _i < 2; ++_i) \
;         __builtin_amdgcn_global_load_lds((const unsigned*)((const char*)(gbase) + (voff)[_i]), (LAS unsigned*)(lds + (bufoff) + ldsw + _i * 8192), 16, 0, 0); } while (0)
; #define G_LDA(dst, b, h) do { _Pragma("unroll") for (int m = 0; m < 4; ++m) _Pragma("unroll") for (int k = 0; k < 2; ++k) dst[m][k] = *(const LAS bf16x8*)(lds + G_SA(b, h) + aoff + m * 2048 + k * 1024); } while (0)
; #define G_LDB(dst, b, h) do { _Pragma("unroll") for (int n = 0; n < 2; ++n) _Pragma("unroll") for (int k = 0; k < 2; ++k) dst[n][k] = *(const LAS bf16x8*)(lds + G_SB(b, h) + boff + n * 2048 + k * 1024); } while (0)
; #define G_MMA(ai, bj, At, Bt) do { __builtin_amdgcn_s_setprio(1); _Pragma("unroll") for (int m = 0; m < 4; ++m) _Pragma("unroll") for (int n = 0; n < 2; ++n) _Pragma("unroll") for (int k = 0; k < 2; ++k) \
;         acc[ai][bj][m][n] = __builtin_amdgcn_mfma_f32_16x16x32_bf16(Bt[n][k], At[m][k], acc[ai][bj][m][n], 0, 0, 0); __builtin_amdgcn_s_setprio(0); } while (0)
; #define G_WAIT_L(n) asm volatile("s_waitcnt lgkmcnt(" #n ")" ::: "memory")
; #define G_BAR __builtin_amdgcn_s_barrier()
; #define G_SCHED __builtin_amdgcn_sched_barrier(0)
;   DI const char* aptr(const Unit& u) const { return (const char*)(h + (size_t)u.pm * 256 * DM); }
; template <class J>
; DI void gemm_phase(LAS unsigned char* lds, const J& job) {
;     ...
;     const bool has_next = job.next(ui + 1, nxt);
;     const char* nA = has_next ? job.aptr(nxt) : cA; const char* nB = has_next ? job.bptr(nxt) : cB;
;     for (int t = 0; t < nt; t += 2) {
;       const bool last = (t == nt - 2);
;       const char* a1 = cA + G_KT(t + 1);
;       const char* a2 = last ? nA + G_KT(0) : cA + G_KT(t + 2); const char* b2 = last ? nB + G_KT(0) : cB + G_KT(t + 2);
;       const char* a3 = last ? nA + G_KT(1) : cA + G_KT(t + 3); const char* b3 = last ? nB + G_KT(1) : cB + G_KT(t + 3);
;       G_LDB(B0, 0, 0); G_SCHED; G_LDA(At, 0, 0); G_STAGE(G_SA(1, 1), a1 + hstepA, voffA);
;       G_WAIT_L(8); G_BAR; G_WAIT_L(0); G_MMA(0, 0, At, B0); G_BAR; G_SCHED;
;       G_LDB(B1, 0, 1); G_STAGE(G_SB(0, 0), b2, voffB);
;       G_BAR; G_WAIT_L(0); G_MMA(0, 1, At, B1); G_BAR;
;       G_LDA(At, 0, 1); G_STAGE(G_SA(0, 0), a2, voffA);
;       G_BAR; G_WAIT_L(0); G_MMA(1, 0, At, B0); G_BAR; G_SCHED;
.LBB0_104:
	s_add_i32 s1, s56, 0xffffff80
	s_and_b32 s0, s7, 0x380
	s_and_b32 s1, s1, 0x380
	s_add_u32 s57, s64, s1
	s_addc_u32 s66, s65, 0
	s_add_u32 s1, s62, s1
	s_addc_u32 s67, s63, 0
	s_and_b32 s68, s56, 0x380
	s_add_u32 s80, s64, s68
	s_addc_u32 s69, s65, 0
	s_add_u32 s97, s62, s68
	s_addc_u32 vcc_lo, s63, 0
	s_cmp_eq_u32 s6, 4
	s_cselect_b32 s71, s83, s66
	s_cselect_b32 s70, s47, s57
	s_cselect_b32 s73, s87, s67
	s_cselect_b32 s72, s86, s1
	s_cselect_b32 s69, s94, s69
	s_cselect_b32 s68, s33, s80
	s_cselect_b32 s67, s5, vcc_lo
	s_cselect_b32 s66, s96, s97
	s_add_i32 s1, s84, 0x100
	v_add_u32_e32 v134, s1, v138
	ds_read_b128 v[140:143], v134
	ds_read_b128 v[148:151], v134 offset:1024
	ds_read_b128 v[152:155], v134 offset:2048
	ds_read_b128 v[156:159], v134 offset:3072
	s_add_u32 vcc_lo, s9, s0
	s_addc_u32 vcc_hi, s17, 0
	v_lshl_add_u64 v[134:135], vcc, 0, v[132:133]
	s_add_i32 m0, s25, 0xc000
	ds_read_b128 v[160:163], v139
	ds_read_b128 v[164:167], v139 offset:1024
	ds_read_b128 v[168:171], v139 offset:2048
	ds_read_b128 v[172:175], v139 offset:3072
	ds_read_b128 v[176:179], v139 offset:4096
	ds_read_b128 v[180:183], v139 offset:5120
	ds_read_b128 v[184:187], v139 offset:6144
	ds_read_b128 v[188:191], v139 offset:7168
	global_load_lds_dwordx4 v[134:135], off
	v_lshl_add_u64 v[134:135], vcc, 0, v[130:131]
	s_add_i32 m0, s25, 0xe000
	s_nop 0
	global_load_lds_dwordx4 v[134:135], off
	s_waitcnt lgkmcnt(8)
	s_barrier
	s_waitcnt lgkmcnt(0)
	v_mfma_f32_16x16x32_bf16 v[124:127], v[140:143], v[160:163], v[124:127]
	v_mfma_f32_16x16x32_bf16 v[120:123], v[152:155], v[160:163], v[120:123]
	v_mfma_f32_16x16x32_bf16 v[116:119], v[140:143], v[168:171], v[116:119]
	v_mfma_f32_16x16x32_bf16 v[108:111], v[152:155], v[168:171], v[108:111]
	v_mfma_f32_16x16x32_bf16 v[100:103], v[140:143], v[176:179], v[100:103]
	v_mfma_f32_16x16x32_bf16 v[92:95], v[152:155], v[176:179], v[92:95]
	v_mfma_f32_16x16x32_bf16 v[84:87], v[140:143], v[184:187], v[84:87]
	v_mfma_f32_16x16x32_bf16 v[76:79], v[152:155], v[184:187], v[76:79]
	v_mfma_f32_16x16x32_bf16 v[124:127], v[148:151], v[164:167], v[124:127]
	v_mfma_f32_16x16x32_bf16 v[120:123], v[156:159], v[164:167], v[120:123]
	v_mfma_f32_16x16x32_bf16 v[116:119], v[148:151], v[172:175], v[116:119]
	v_mfma_f32_16x16x32_bf16 v[108:111], v[156:159], v[172:175], v[108:111]
	v_mfma_f32_16x16x32_bf16 v[100:103], v[148:151], v[180:183], v[100:103]
	v_mfma_f32_16x16x32_bf16 v[92:95], v[156:159], v[180:183], v[92:95]
	v_mfma_f32_16x16x32_bf16 v[84:87], v[148:151], v[188:191], v[84:87]
	v_mfma_f32_16x16x32_bf16 v[76:79], v[156:159], v[188:191], v[76:79]
	s_barrier
	s_add_i32 s0, s85, 0x100
	v_add_u32_e32 v134, s0, v138
	s_add_i32 s1, s1, s24
	ds_read_b128 v[192:195], v134
	ds_read_b128 v[196:199], v134 offset:1024
	ds_read_b128 v[200:203], v134 offset:2048
	ds_read_b128 v[204:207], v134 offset:3072
	v_lshl_add_u64 v[134:135], s[72:73], 0, v[146:147]
	s_mov_b32 m0, s1
	s_nop 0
	global_load_lds_dwordx4 v[134:135], off
	v_lshl_add_u64 v[134:135], s[72:73], 0, v[128:129]
	s_add_i32 m0, s1, 0x2000
	s_nop 0
	global_load_lds_dwordx4 v[134:135], off
	s_barrier
	s_waitcnt lgkmcnt(0)
	v_mfma_f32_16x16x32_bf16 v[112:115], v[192:195], v[160:163], v[112:115]
	v_mfma_f32_16x16x32_bf16 v[104:107], v[200:203], v[160:163], v[104:107]
	v_mfma_f32_16x16x32_bf16 v[96:99], v[192:195], v[168:171], v[96:99]
	v_mfma_f32_16x16x32_bf16 v[88:91], v[200:203], v[168:171], v[88:91]
	v_mfma_f32_16x16x32_bf16 v[80:83], v[192:195], v[176:179], v[80:83]
	v_mfma_f32_16x16x32_bf16 v[72:75], v[200:203], v[176:179], v[72:75]
	v_mfma_f32_16x16x32_bf16 v[68:71], v[192:195], v[184:187], v[68:71]
	v_mfma_f32_16x16x32_bf16 v[64:67], v[200:203], v[184:187], v[64:67]
	v_mfma_f32_16x16x32_bf16 v[112:115], v[196:199], v[164:167], v[112:115]
	v_mfma_f32_16x16x32_bf16 v[104:107], v[204:207], v[164:167], v[104:107]
	v_mfma_f32_16x16x32_bf16 v[96:99], v[196:199], v[172:175], v[96:99]
	v_mfma_f32_16x16x32_bf16 v[88:91], v[204:207], v[172:175], v[88:91]
	v_mfma_f32_16x16x32_bf16 v[80:83], v[196:199], v[180:183], v[80:83]
	v_mfma_f32_16x16x32_bf16 v[72:75], v[204:207], v[180:183], v[72:75]
	v_mfma_f32_16x16x32_bf16 v[68:71], v[196:199], v[188:191], v[68:71]
	v_mfma_f32_16x16x32_bf16 v[64:67], v[204:207], v[188:191], v[64:67]
	s_mov_b32 m0, s25
	v_lshl_add_u64 v[134:135], s[70:71], 0, v[132:133]
	s_barrier
	ds_read_b128 v[160:163], v139 offset:16384
	ds_read_b128 v[164:167], v139 offset:17408
	ds_read_b128 v[168:171], v139 offset:18432
	ds_read_b128 v[172:175], v139 offset:19456
	ds_read_b128 v[176:179], v139 offset:20480
	ds_read_b128 v[180:183], v139 offset:21504
	ds_read_b128 v[184:187], v139 offset:22528
	ds_read_b128 v[188:191], v139 offset:23552
	global_load_lds_dwordx4 v[134:135], off
	v_lshl_add_u64 v[134:135], s[70:71], 0, v[130:131]
	s_mov_b32 m0, s36
	s_nop 0
	global_load_lds_dwordx4 v[134:135], off
	s_barrier
	s_waitcnt lgkmcnt(0)
	v_mfma_f32_16x16x32_bf16 v[60:63], v[140:143], v[160:163], v[60:63]
	v_mfma_f32_16x16x32_bf16 v[56:59], v[152:155], v[160:163], v[56:59]
	v_mfma_f32_16x16x32_bf16 v[52:55], v[140:143], v[168:171], v[52:55]
	v_mfma_f32_16x16x32_bf16 v[44:47], v[152:155], v[168:171], v[44:47]
	v_mfma_f32_16x16x32_bf16 v[36:39], v[140:143], v[176:179], v[36:39]
	v_mfma_f32_16x16x32_bf16 v[28:31], v[152:155], v[176:179], v[28:31]
	v_mfma_f32_16x16x32_bf16 v[20:23], v[140:143], v[184:187], v[20:23]
	v_mfma_f32_16x16x32_bf16 v[12:15], v[152:155], v[184:187], v[12:15]
	v_mfma_f32_16x16x32_bf16 v[60:63], v[148:151], v[164:167], v[60:63]
	v_mfma_f32_16x16x32_bf16 v[56:59], v[156:159], v[164:167], v[56:59]
	v_mfma_f32_16x16x32_bf16 v[52:55], v[148:151], v[172:175], v[52:55]
	v_mfma_f32_16x16x32_bf16 v[44:47], v[156:159], v[172:175], v[44:47]
	v_mfma_f32_16x16x32_bf16 v[36:39], v[148:151], v[180:183], v[36:39]
	v_mfma_f32_16x16x32_bf16 v[28:31], v[156:159], v[180:183], v[28:31]
	v_mfma_f32_16x16x32_bf16 v[20:23], v[148:151], v[188:191], v[20:23]
	v_mfma_f32_16x16x32_bf16 v[12:15], v[156:159], v[188:191], v[12:15]
	s_barrier
; #define G_STAGE(bufoff, gbase, voff) do { _Pragma("unroll") for (int _i = 0; _i < 2; ++_i) \
;         __builtin_amdgcn_global_load_lds((const unsigned*)((const char*)(gbase) + (voff)[_i]), (LAS unsigned*)(lds + (bufoff) + ldsw + _i * 8192), 16, 0, 0); } while (0)
; #define G_LDA(dst, b, h) do { _Pragma("unroll") for (int m = 0; m < 4; ++m) _Pragma("unroll") for (int k = 0; k < 2; ++k) dst[m][k] = *(const LAS bf16x8*)(lds + G_SA(b, h) + aoff + m * 2048 + k * 1024); } while (0)
; #define G_LDB(dst, b, h) do { _Pragma("unroll") for (int n = 0; n < 2; ++n) _Pragma("unroll") for (int k = 0; k < 2; ++k) dst[n][k] = *(const LAS bf16x8*)(lds + G_SB(b, h) + boff + n * 2048 + k * 1024); } while (0)
; #define G_MMA(ai, bj, At, Bt) do { __builtin_amdgcn_s_setprio(1); _Pragma("unroll") for (int m = 0; m < 4; ++m) _Pragma("unroll") for (int n = 0; n < 2; ++n) _Pragma("unroll") for (int k = 0; k < 2; ++k) \
;         acc[ai][bj][m][n] = __builtin_amdgcn_mfma_f32_16x16x32_bf16(Bt[n][k], At[m][k], acc[ai][bj][m][n], 0, 0, 0); __builtin_amdgcn_s_setprio(0); } while (0)
; #define G_WAIT_V(n) asm volatile("s_waitcnt vmcnt(" #n ")" ::: "memory")
; #define G_WAIT_L(n) asm volatile("s_waitcnt lgkmcnt(" #n ")" ::: "memory")
; #define G_BAR __builtin_amdgcn_s_barrier()
; #define G_SCHED __builtin_amdgcn_sched_barrier(0)
; template <class J>
; DI void gemm_phase(LAS unsigned char* lds, const J& job) {
;     ...
;       G_STAGE(G_SB(0, 1), b2 + hstepB, voffB);
;       G_WAIT_V(6); G_BAR; G_MMA(1, 1, At, B1); G_BAR;
;       G_LDB(B0, 1, 0); G_SCHED; G_LDA(At, 1, 0); G_STAGE(G_SA(0, 1), a2 + hstepA, voffA);
;       G_WAIT_L(8); G_BAR; G_WAIT_L(0); G_MMA(0, 0, At, B0); G_BAR; G_SCHED;
;       G_LDB(B1, 1, 1); G_STAGE(G_SB(1, 0), b3, voffB);
;       G_BAR; G_WAIT_L(0); G_MMA(0, 1, At, B1); G_BAR;
;       G_LDA(At, 1, 1); G_STAGE(G_SA(1, 0), a3, voffA);
	s_add_u32 s72, s72, 0x20000
	s_addc_u32 s73, s73, 0
	s_add_i32 s0, s0, s24
	v_lshl_add_u64 v[134:135], s[72:73], 0, v[146:147]
	s_mov_b32 m0, s0
	s_nop 0
	global_load_lds_dwordx4 v[134:135], off
	v_lshl_add_u64 v[134:135], s[72:73], 0, v[128:129]
	s_add_i32 m0, s0, 0x2000
	s_nop 0
	global_load_lds_dwordx4 v[134:135], off
	s_waitcnt vmcnt(6)
	s_barrier
	v_mfma_f32_16x16x32_bf16 v[48:51], v[192:195], v[160:163], v[48:51]
	v_mfma_f32_16x16x32_bf16 v[40:43], v[200:203], v[160:163], v[40:43]
	v_mfma_f32_16x16x32_bf16 v[32:35], v[192:195], v[168:171], v[32:35]
	v_mfma_f32_16x16x32_bf16 v[24:27], v[200:203], v[168:171], v[24:27]
	v_mfma_f32_16x16x32_bf16 v[16:19], v[192:195], v[176:179], v[16:19]
	v_mfma_f32_16x16x32_bf16 v[8:11], v[200:203], v[176:179], v[8:11]
	v_mfma_f32_16x16x32_bf16 v[4:7], v[192:195], v[184:187], v[4:7]
	v_mfma_f32_16x16x32_bf16 v[0:3], v[200:203], v[184:187], v[0:3]
	v_mfma_f32_16x16x32_bf16 v[48:51], v[196:199], v[164:167], v[48:51]
	v_mfma_f32_16x16x32_bf16 v[40:43], v[204:207], v[164:167], v[40:43]
	v_mfma_f32_16x16x32_bf16 v[32:35], v[196:199], v[172:175], v[32:35]
	v_mfma_f32_16x16x32_bf16 v[24:27], v[204:207], v[172:175], v[24:27]
	v_mfma_f32_16x16x32_bf16 v[16:19], v[196:199], v[180:183], v[16:19]
	v_mfma_f32_16x16x32_bf16 v[8:11], v[204:207], v[180:183], v[8:11]
	v_mfma_f32_16x16x32_bf16 v[4:7], v[196:199], v[188:191], v[4:7]
	v_mfma_f32_16x16x32_bf16 v[0:3], v[204:207], v[188:191], v[0:3]
	s_add_i32 s0, s88, 0x100
	v_add_u32_e32 v134, s0, v138
	s_barrier
	ds_read_b128 v[140:143], v134
	ds_read_b128 v[148:151], v134 offset:1024
	ds_read_b128 v[152:155], v134 offset:2048
	ds_read_b128 v[156:159], v134 offset:3072
	s_add_u32 s70, s70, 0x80000
	s_addc_u32 s71, s71, 0
	s_mov_b32 m0, s37
	v_lshl_add_u64 v[134:135], s[70:71], 0, v[132:133]
	ds_read_b128 v[160:163], v139 offset:32768
	ds_read_b128 v[164:167], v139 offset:33792
	ds_read_b128 v[168:171], v139 offset:34816
	ds_read_b128 v[172:175], v139 offset:35840
	ds_read_b128 v[176:179], v139 offset:36864
	ds_read_b128 v[180:183], v139 offset:37888
	ds_read_b128 v[184:187], v139 offset:38912
	ds_read_b128 v[188:191], v139 offset:39936
	global_load_lds_dwordx4 v[134:135], off
	v_lshl_add_u64 v[134:135], s[70:71], 0, v[130:131]
	s_mov_b32 m0, s38
	s_nop 0
	global_load_lds_dwordx4 v[134:135], off
	s_waitcnt lgkmcnt(8)
	s_barrier
	s_waitcnt lgkmcnt(0)
	v_mfma_f32_16x16x32_bf16 v[124:127], v[140:143], v[160:163], v[124:127]
	v_mfma_f32_16x16x32_bf16 v[120:123], v[152:155], v[160:163], v[120:123]
	v_mfma_f32_16x16x32_bf16 v[116:119], v[140:143], v[168:171], v[116:119]
	v_mfma_f32_16x16x32_bf16 v[108:111], v[152:155], v[168:171], v[108:111]
	v_mfma_f32_16x16x32_bf16 v[100:103], v[140:143], v[176:179], v[100:103]
	v_mfma_f32_16x16x32_bf16 v[92:95], v[152:155], v[176:179], v[92:95]
	v_mfma_f32_16x16x32_bf16 v[84:87], v[140:143], v[184:187], v[84:87]
	v_mfma_f32_16x16x32_bf16 v[76:79], v[152:155], v[184:187], v[76:79]
	v_mfma_f32_16x16x32_bf16 v[124:127], v[148:151], v[164:167], v[124:127]
	v_mfma_f32_16x16x32_bf16 v[120:123], v[156:159], v[164:167], v[120:123]
	v_mfma_f32_16x16x32_bf16 v[116:119], v[148:151], v[172:175], v[116:119]
	v_mfma_f32_16x16x32_bf16 v[108:111], v[156:159], v[172:175], v[108:111]
	v_mfma_f32_16x16x32_bf16 v[100:103], v[148:151], v[180:183], v[100:103]
	v_mfma_f32_16x16x32_bf16 v[92:95], v[156:159], v[180:183], v[92:95]
	v_mfma_f32_16x16x32_bf16 v[84:87], v[148:151], v[188:191], v[84:87]
	v_mfma_f32_16x16x32_bf16 v[76:79], v[156:159], v[188:191], v[76:79]
	s_barrier
	s_add_i32 s1, s89, 0x100
	v_add_u32_e32 v134, s1, v138
	s_add_i32 s0, s0, s24
	ds_read_b128 v[192:195], v134
	ds_read_b128 v[196:199], v134 offset:1024
	ds_read_b128 v[200:203], v134 offset:2048
	ds_read_b128 v[204:207], v134 offset:3072
	v_lshl_add_u64 v[134:135], s[66:67], 0, v[146:147]
	s_mov_b32 m0, s0
	s_nop 0
	global_load_lds_dwordx4 v[134:135], off
	v_lshl_add_u64 v[134:135], s[66:67], 0, v[128:129]
	s_add_i32 m0, s0, 0x2000
	s_nop 0
	global_load_lds_dwordx4 v[134:135], off
	s_barrier
	s_waitcnt lgkmcnt(0)
	v_mfma_f32_16x16x32_bf16 v[112:115], v[192:195], v[160:163], v[112:115]
	v_mfma_f32_16x16x32_bf16 v[104:107], v[200:203], v[160:163], v[104:107]
	v_mfma_f32_16x16x32_bf16 v[96:99], v[192:195], v[168:171], v[96:99]
	v_mfma_f32_16x16x32_bf16 v[88:91], v[200:203], v[168:171], v[88:91]
	v_mfma_f32_16x16x32_bf16 v[80:83], v[192:195], v[176:179], v[80:83]
	v_mfma_f32_16x16x32_bf16 v[72:75], v[200:203], v[176:179], v[72:75]
	v_mfma_f32_16x16x32_bf16 v[68:71], v[192:195], v[184:187], v[68:71]
	v_mfma_f32_16x16x32_bf16 v[64:67], v[200:203], v[184:187], v[64:67]
	v_mfma_f32_16x16x32_bf16 v[112:115], v[196:199], v[164:167], v[112:115]
	v_mfma_f32_16x16x32_bf16 v[104:107], v[204:207], v[164:167], v[104:107]
	v_mfma_f32_16x16x32_bf16 v[96:99], v[196:199], v[172:175], v[96:99]
	v_mfma_f32_16x16x32_bf16 v[88:91], v[204:207], v[172:175], v[88:91]
	v_mfma_f32_16x16x32_bf16 v[80:83], v[196:199], v[180:183], v[80:83]
	v_mfma_f32_16x16x32_bf16 v[72:75], v[204:207], v[180:183], v[72:75]
	v_mfma_f32_16x16x32_bf16 v[68:71], v[196:199], v[188:191], v[68:71]
	v_mfma_f32_16x16x32_bf16 v[64:67], v[204:207], v[188:191], v[64:67]
	s_mov_b32 m0, s75
	v_lshl_add_u64 v[134:135], s[68:69], 0, v[132:133]
	s_barrier
	ds_read_b128 v[160:163], v139 offset:49152
	ds_read_b128 v[164:167], v139 offset:50176
	ds_read_b128 v[168:171], v139 offset:51200
	ds_read_b128 v[172:175], v139 offset:52224
	ds_read_b128 v[176:179], v139 offset:53248
	ds_read_b128 v[180:183], v139 offset:54272
	ds_read_b128 v[184:187], v139 offset:55296
	ds_read_b128 v[188:191], v139 offset:56320
	global_load_lds_dwordx4 v[134:135], off
	v_lshl_add_u64 v[134:135], s[68:69], 0, v[130:131]
	s_mov_b32 m0, s76
	s_nop 0
	global_load_lds_dwordx4 v[134:135], off
	s_barrier
; #define G_STAGE(bufoff, gbase, voff) do { _Pragma("unroll") for (int _i = 0; _i < 2; ++_i) \
;         __builtin_amdgcn_global_load_lds((const unsigned*)((const char*)(gbase) + (voff)[_i]), (LAS unsigned*)(lds + (bufoff) + ldsw + _i * 8192), 16, 0, 0); } while (0)
; #define G_MMA(ai, bj, At, Bt) do { __builtin_amdgcn_s_setprio(1); _Pragma("unroll") for (int m = 0; m < 4; ++m) _Pragma("unroll") for (int n = 0; n < 2; ++n) _Pragma("unroll") for (int k = 0; k < 2; ++k) \
;         acc[ai][bj][m][n] = __builtin_amdgcn_mfma_f32_16x16x32_bf16(Bt[n][k], At[m][k], acc[ai][bj][m][n], 0, 0, 0); __builtin_amdgcn_s_setprio(0); } while (0)
; #define G_WAIT_V(n) asm volatile("s_waitcnt vmcnt(" #n ")" ::: "memory")
; #define G_WAIT_L(n) asm volatile("s_waitcnt lgkmcnt(" #n ")" ::: "memory")
; #define G_BAR __builtin_amdgcn_s_barrier()
; #define G_SCHED __builtin_amdgcn_sched_barrier(0)
; template <class J>
; DI void gemm_phase(LAS unsigned char* lds, const J& job) {
;     ...
;       G_BAR; G_WAIT_L(0); G_MMA(1, 0, At, B0); G_BAR; G_SCHED;
;       G_STAGE(G_SB(1, 1), b3 + hstepB, voffB);
;       G_WAIT_V(6); G_BAR; G_MMA(1, 1, At, B1); G_BAR;
;     }
	s_waitcnt lgkmcnt(0)
	v_mfma_f32_16x16x32_bf16 v[60:63], v[140:143], v[160:163], v[60:63]
	v_mfma_f32_16x16x32_bf16 v[56:59], v[152:155], v[160:163], v[56:59]
	v_mfma_f32_16x16x32_bf16 v[52:55], v[140:143], v[168:171], v[52:55]
	v_mfma_f32_16x16x32_bf16 v[44:47], v[152:155], v[168:171], v[44:47]
	v_mfma_f32_16x16x32_bf16 v[36:39], v[140:143], v[176:179], v[36:39]
	v_mfma_f32_16x16x32_bf16 v[28:31], v[152:155], v[176:179], v[28:31]
	v_mfma_f32_16x16x32_bf16 v[20:23], v[140:143], v[184:187], v[20:23]
	v_mfma_f32_16x16x32_bf16 v[12:15], v[152:155], v[184:187], v[12:15]
	v_mfma_f32_16x16x32_bf16 v[60:63], v[148:151], v[164:167], v[60:63]
	v_mfma_f32_16x16x32_bf16 v[56:59], v[156:159], v[164:167], v[56:59]
	v_mfma_f32_16x16x32_bf16 v[52:55], v[148:151], v[172:175], v[52:55]
	v_mfma_f32_16x16x32_bf16 v[44:47], v[156:159], v[172:175], v[44:47]
	v_mfma_f32_16x16x32_bf16 v[36:39], v[148:151], v[180:183], v[36:39]
	v_mfma_f32_16x16x32_bf16 v[28:31], v[156:159], v[180:183], v[28:31]
	v_mfma_f32_16x16x32_bf16 v[20:23], v[148:151], v[188:191], v[20:23]
	v_mfma_f32_16x16x32_bf16 v[12:15], v[156:159], v[188:191], v[12:15]
	s_barrier
	s_add_u32 s66, s66, 0x20000
	s_addc_u32 s67, s67, 0
	s_add_i32 s0, s1, s24
	v_lshl_add_u64 v[134:135], s[66:67], 0, v[146:147]
	s_mov_b32 m0, s0
	s_nop 0
	global_load_lds_dwordx4 v[134:135], off
	v_lshl_add_u64 v[134:135], s[66:67], 0, v[128:129]
	s_add_i32 m0, s0, 0x2000
	s_nop 0
	global_load_lds_dwordx4 v[134:135], off
	s_waitcnt vmcnt(6)
	s_barrier
	v_mfma_f32_16x16x32_bf16 v[48:51], v[192:195], v[160:163], v[48:51]
	v_mfma_f32_16x16x32_bf16 v[40:43], v[200:203], v[160:163], v[40:43]
	v_mfma_f32_16x16x32_bf16 v[32:35], v[192:195], v[168:171], v[32:35]
	v_mfma_f32_16x16x32_bf16 v[24:27], v[200:203], v[168:171], v[24:27]
	v_mfma_f32_16x16x32_bf16 v[16:19], v[192:195], v[176:179], v[16:19]
	v_mfma_f32_16x16x32_bf16 v[8:11], v[200:203], v[176:179], v[8:11]
	v_mfma_f32_16x16x32_bf16 v[4:7], v[192:195], v[184:187], v[4:7]
	v_mfma_f32_16x16x32_bf16 v[0:3], v[200:203], v[184:187], v[0:3]
	v_mfma_f32_16x16x32_bf16 v[48:51], v[196:199], v[164:167], v[48:51]
	v_mfma_f32_16x16x32_bf16 v[40:43], v[204:207], v[164:167], v[40:43]
	v_mfma_f32_16x16x32_bf16 v[32:35], v[196:199], v[172:175], v[32:35]
	v_mfma_f32_16x16x32_bf16 v[24:27], v[204:207], v[172:175], v[24:27]
	v_mfma_f32_16x16x32_bf16 v[16:19], v[196:199], v[180:183], v[16:19]
	v_mfma_f32_16x16x32_bf16 v[8:11], v[204:207], v[180:183], v[8:11]
	v_mfma_f32_16x16x32_bf16 v[4:7], v[196:199], v[188:191], v[4:7]
	v_mfma_f32_16x16x32_bf16 v[0:3], v[204:207], v[188:191], v[0:3]
	s_add_i32 s6, s6, 2
	s_addk_i32 s56, 0x100
	s_addk_i32 s7, 0x100
	s_cmp_gt_u32 s6, 5
	s_barrier
	s_cbranch_scc0 .LBB0_104
; DI unsigned pk2(float lo, float hi) { unsigned r; asm("v_cvt_pk_bf16_f32 %0, %1, %2" : "=v"(r) : "v"(lo), "v"(hi)); return r; }
; #define G_WAIT_V(n) asm volatile("s_waitcnt vmcnt(" #n ")" ::: "memory")
; #define G_BAR __builtin_amdgcn_s_barrier()
; template <class J>
; DI void gemm_phase(LAS unsigned char* lds, const J& job) {
;     ...
;     if (!has_next) break;
; #pragma unroll
;     for (int a = 0; a < 2; ++a)
; #pragma unroll
;       for (int b = 0; b < 2; ++b)
; #pragma unroll
;         for (int m = 0; m < 4; ++m)
; #pragma unroll
;           for (int n = 0; n < 2; ++n) acc[a][b][m][n] = (f32x4){0.f, 0.f, 0.f, 0.f};
;     cur = nxt; cA = nA; cB = nB; ++ui;
;   }
;   G_WAIT_V(0);
;   if (wr == 0) G_BAR;
;   DI void epi(const Acc& acc, const Unit& u, int wr, int wc, int fr, int fq) const {
;     ...
;     for (int ai = 0; ai < 2; ++ai)
; #pragma unroll
;       for (int m = 0; m < 4; ++m) {
;         const int row = u.pm * 256 + ai * HALF + wr * 64 + m * 16 + fr;
; #pragma unroll
;         for (int bj = 0; bj < 2; ++bj) {
;           const int col = u.pn * 256 + bj * HALF + wc * 32 + 8 * fq;
;           const f32x4 v0 = acc[ai][bj][m][0], v1 = acc[ai][bj][m][1];
;           u32x4 o; o.x = pk2(v0.x, v0.y); o.y = pk2(v0.z, v0.w); o.z = pk2(v1.x, v1.y); o.w = pk2(v1.z, v1.w);
;           *(u32x4*)(Z + (size_t)row * NGATE + col) = o;
;         }
	v_mov_b32_e32 v135, v137
	v_mov_b32_e32 v134, v136
	s_lshl_b32 s0, s22, 8
	s_add_i32 s0, s0, s44
	v_add_u32_e32 v134, s0, v134
	s_lshl_b32 s0, s46, 8
	s_or_b32 s0, s0, s45
	v_cvt_pk_bf16_f32 v68, v68, v69
	v_cvt_pk_bf16_f32 v69, v70, v71
	v_cvt_pk_bf16_f32 v70, v64, v65
	v_add_u32_e32 v64, 0x80, v134
	v_lshl_add_u32 v140, v135, 3, s0
	v_ashrrev_i32_e32 v135, 31, v134
	v_ashrrev_i32_e32 v65, 31, v64
	v_lshlrev_b64 v[142:143], 14, v[134:135]
	v_ashrrev_i32_e32 v141, 31, v140
	v_lshlrev_b64 v[64:65], 14, v[64:65]
	v_cvt_pk_bf16_f32 v124, v124, v125
	v_cvt_pk_bf16_f32 v125, v126, v127
	v_cvt_pk_bf16_f32 v126, v120, v121
	v_cvt_pk_bf16_f32 v127, v122, v123
	v_lshl_add_u64 v[122:123], s[26:27], 0, v[142:143]
	v_lshlrev_b64 v[120:121], 1, v[140:141]
	v_cvt_pk_bf16_f32 v112, v112, v113
	v_cvt_pk_bf16_f32 v113, v114, v115
	v_cvt_pk_bf16_f32 v114, v104, v105
	v_add_u32_e32 v104, 16, v134
	v_cvt_pk_bf16_f32 v60, v60, v61
	v_cvt_pk_bf16_f32 v61, v62, v63
	v_cvt_pk_bf16_f32 v62, v56, v57
	v_lshl_add_u64 v[56:57], s[26:27], 0, v[64:65]
	v_cvt_pk_bf16_f32 v48, v48, v49
	v_cvt_pk_bf16_f32 v49, v50, v51
	v_cvt_pk_bf16_f32 v50, v40, v41
	v_add_u32_e32 v40, 0x90, v134
	v_lshl_add_u64 v[122:123], v[122:123], 0, v[120:121]
	v_ashrrev_i32_e32 v105, 31, v104
	v_lshl_add_u64 v[56:57], v[56:57], 0, v[120:121]
	v_ashrrev_i32_e32 v41, 31, v40
	v_cvt_pk_bf16_f32 v115, v106, v107
	global_store_dwordx4 v[122:123], v[112:115], off offset:256
	v_cvt_pk_bf16_f32 v51, v42, v43
	global_store_dwordx4 v[56:57], v[48:51], off offset:256
	v_cvt_pk_bf16_f32 v106, v108, v109
	v_cvt_pk_bf16_f32 v96, v96, v97
	v_cvt_pk_bf16_f32 v97, v98, v99
	s_nop 0
	v_lshlrev_b64 v[112:113], 14, v[104:105]
	v_lshl_add_u64 v[108:109], s[26:27], 0, v[112:113]
	v_lshlrev_b64 v[48:49], 14, v[40:41]
	v_cvt_pk_bf16_f32 v98, v88, v89
	v_add_u32_e32 v88, 32, v134
	v_cvt_pk_bf16_f32 v42, v44, v45
	v_lshl_add_u64 v[44:45], s[26:27], 0, v[48:49]
	v_cvt_pk_bf16_f32 v32, v32, v33
	v_cvt_pk_bf16_f32 v33, v34, v35
	v_cvt_pk_bf16_f32 v34, v24, v25
	v_add_u32_e32 v24, 0xa0, v134
	v_lshl_add_u64 v[108:109], v[108:109], 0, v[120:121]
	v_ashrrev_i32_e32 v89, 31, v88
	v_lshl_add_u64 v[44:45], v[44:45], 0, v[120:121]
	v_ashrrev_i32_e32 v25, 31, v24
	v_cvt_pk_bf16_f32 v99, v90, v91
	global_store_dwordx4 v[108:109], v[96:99], off offset:256
	v_cvt_pk_bf16_f32 v35, v26, v27
	global_store_dwordx4 v[44:45], v[32:35], off offset:256
	v_cvt_pk_bf16_f32 v90, v92, v93
	v_cvt_pk_bf16_f32 v80, v80, v81
	v_cvt_pk_bf16_f32 v81, v82, v83
	s_nop 0
	v_lshlrev_b64 v[96:97], 14, v[88:89]
	v_lshl_add_u64 v[92:93], s[26:27], 0, v[96:97]
	v_lshlrev_b64 v[32:33], 14, v[24:25]
	v_cvt_pk_bf16_f32 v82, v72, v73
	v_add_u32_e32 v72, 48, v134
	v_cvt_pk_bf16_f32 v26, v28, v29
	v_lshl_add_u64 v[28:29], s[26:27], 0, v[32:33]
	v_cvt_pk_bf16_f32 v16, v16, v17
	v_cvt_pk_bf16_f32 v17, v18, v19
	v_cvt_pk_bf16_f32 v18, v8, v9
	v_add_u32_e32 v8, 0xb0, v134
	v_lshl_add_u64 v[92:93], v[92:93], 0, v[120:121]
	v_ashrrev_i32_e32 v73, 31, v72
	v_lshl_add_u64 v[28:29], v[28:29], 0, v[120:121]
	v_ashrrev_i32_e32 v9, 31, v8
	v_cvt_pk_bf16_f32 v83, v74, v75
	global_store_dwordx4 v[92:93], v[80:83], off offset:256
	v_cvt_pk_bf16_f32 v19, v10, v11
	global_store_dwordx4 v[28:29], v[16:19], off offset:256
	v_cvt_pk_bf16_f32 v74, v76, v77
	v_cvt_pk_bf16_f32 v10, v12, v13
	s_and_b64 vcc, exec, s[12:13]
	v_lshlrev_b64 v[80:81], 14, v[72:73]
	v_lshlrev_b64 v[16:17], 14, v[8:9]
	v_lshl_add_u64 v[76:77], s[26:27], 0, v[80:81]
	v_lshl_add_u64 v[12:13], s[26:27], 0, v[16:17]
	v_lshl_add_u64 v[76:77], v[76:77], 0, v[120:121]
	v_lshl_add_u64 v[12:13], v[12:13], 0, v[120:121]
	s_mov_b32 s46, s8
	s_mov_b32 s22, s16
	s_mov_b64 s[62:63], s[20:21]
	s_mov_b64 s[64:65], s[18:19]
	global_store_dwordx4 v[122:123], v[124:127], off
	v_cvt_pk_bf16_f32 v104, v116, v117
	v_cvt_pk_bf16_f32 v105, v118, v119
	v_cvt_pk_bf16_f32 v107, v110, v111
	global_store_dwordx4 v[108:109], v[104:107], off
	v_cvt_pk_bf16_f32 v88, v100, v101
	v_cvt_pk_bf16_f32 v89, v102, v103
	v_cvt_pk_bf16_f32 v91, v94, v95
	global_store_dwordx4 v[92:93], v[88:91], off
	v_cvt_pk_bf16_f32 v72, v84, v85
	v_cvt_pk_bf16_f32 v73, v86, v87
	v_cvt_pk_bf16_f32 v75, v78, v79
	global_store_dwordx4 v[76:77], v[72:75], off
	v_cvt_pk_bf16_f32 v71, v66, v67
	global_store_dwordx4 v[76:77], v[68:71], off offset:256
	v_cvt_pk_bf16_f32 v63, v58, v59
	global_store_dwordx4 v[56:57], v[60:63], off
	v_cvt_pk_bf16_f32 v40, v52, v53
	v_cvt_pk_bf16_f32 v41, v54, v55
	v_cvt_pk_bf16_f32 v43, v46, v47
	global_store_dwordx4 v[44:45], v[40:43], off
	v_cvt_pk_bf16_f32 v24, v36, v37
	v_cvt_pk_bf16_f32 v25, v38, v39
	v_cvt_pk_bf16_f32 v27, v30, v31
	global_store_dwordx4 v[28:29], v[24:27], off
	v_cvt_pk_bf16_f32 v8, v20, v21
	v_cvt_pk_bf16_f32 v9, v22, v23
	v_cvt_pk_bf16_f32 v11, v14, v15
	global_store_dwordx4 v[12:13], v[8:11], off
	v_cvt_pk_bf16_f32 v4, v4, v5
	v_cvt_pk_bf16_f32 v5, v6, v7
	v_cvt_pk_bf16_f32 v6, v0, v1
	v_cvt_pk_bf16_f32 v7, v2, v3
	global_store_dwordx4 v[12:13], v[4:7], off offset:256
	s_cbranch_vccz .LBB0_101
	s_setprio 0
	s_waitcnt vmcnt(0)
	v_readlane_b32 s44, v255, 6
	s_cmpk_gt_u32 s4, 0xff
	v_readlane_b32 s45, v255, 7
	s_cbranch_scc1 .LBB0_108
	s_barrier

; #define G_STAGE(bufoff, gbase, voff) do { _Pragma("unroll") for (int _i = 0; _i < 2; ++_i) \
;         __builtin_amdgcn_global_load_lds((const unsigned*)((const char*)(gbase) + (voff)[_i]), (LAS unsigned*)(lds + (bufoff) + ldsw + _i * 8192), 16, 0, 0); } while (0)
; #define G_LDA(dst, b, h) do { _Pragma("unroll") for (int m = 0; m < 4; ++m) _Pragma("unroll") for (int k = 0; k < 2; ++k) dst[m][k] = *(const LAS bf16x8*)(lds + G_SA(b, h) + aoff + m * 2048 + k * 1024); } while (0)
; #define G_LDB(dst, b, h) do { _Pragma("unroll") for (int n = 0; n < 2; ++n) _Pragma("unroll") for (int k = 0; k < 2; ++k) dst[n][k] = *(const LAS bf16x8*)(lds + G_SB(b, h) + boff + n * 2048 + k * 1024); } while (0)
; #define G_MMA(ai, bj, At, Bt) do { __builtin_amdgcn_s_setprio(1); _Pragma("unroll") for (int m = 0; m < 4; ++m) _Pragma("unroll") for (int n = 0; n < 2; ++n) _Pragma("unroll") for (int k = 0; k < 2; ++k) \
;         acc[ai][bj][m][n] = __builtin_amdgcn_mfma_f32_16x16x32_bf16(Bt[n][k], At[m][k], acc[ai][bj][m][n], 0, 0, 0); __builtin_amdgcn_s_setprio(0); } while (0)
; #define G_WAIT_V(n) asm volatile("s_waitcnt vmcnt(" #n ")" ::: "memory")
; #define G_WAIT_L(n) asm volatile("s_waitcnt lgkmcnt(" #n ")" ::: "memory")
; #define G_BAR __builtin_amdgcn_s_barrier()
; template <class J>
; DI void gemm_phase(LAS unsigned char* lds, const J& job) {
;     ...
;       const bool last = (t == nt - 2);
;       const char* a1 = cA + G_KT(t + 1);
;       const char* a2 = last ? nA + G_KT(0) : cA + G_KT(t + 2); const char* b2 = last ? nB + G_KT(0) : cB + G_KT(t + 2);
;       const char* a3 = last ? nA + G_KT(1) : cA + G_KT(t + 3); const char* b3 = last ? nB + G_KT(1) : cB + G_KT(t + 3);
;       G_LDB(B0, 0, 0); G_SCHED; G_LDA(At, 0, 0); G_STAGE(G_SA(1, 1), a1 + hstepA, voffA);
;       G_WAIT_L(8); G_BAR; G_WAIT_L(0); G_MMA(0, 0, At, B0); G_BAR; G_SCHED;
;       G_LDB(B1, 0, 1); G_STAGE(G_SB(0, 0), b2, voffB);
;       G_BAR; G_WAIT_L(0); G_MMA(0, 1, At, B1); G_BAR;
;       G_LDA(At, 0, 1); G_STAGE(G_SA(0, 0), a2, voffA);
;       G_BAR; G_WAIT_L(0); G_MMA(1, 0, At, B0); G_BAR; G_SCHED;
;       G_STAGE(G_SB(0, 1), b2 + hstepB, voffB);
;       G_WAIT_V(6); G_BAR; G_MMA(1, 1, At, B1); G_BAR;
;       G_LDB(B0, 1, 0); G_SCHED; G_LDA(At, 1, 0); G_STAGE(G_SA(0, 1), a2 + hstepA, voffA);
;       G_WAIT_L(8); G_BAR; G_WAIT_L(0); G_MMA(0, 0, At, B0); G_BAR; G_SCHED;
.LBB0_282:
	s_add_i32 s1, s56, 0xffffff80
	s_and_b32 s0, s7, 0xf80
	s_and_b32 s1, s1, 0xf00
	s_add_u32 s10, s68, s1
	s_addc_u32 s11, s69, 0
	s_add_u32 s1, s66, s1
	s_addc_u32 s57, s67, 0
	s_and_b32 s70, s56, 0xf80
	s_add_u32 s71, s68, s70
	s_addc_u32 s72, s69, 0
	s_add_u32 s70, s66, s70
	s_addc_u32 s80, s67, 0
	s_cmp_eq_u32 s6, 28
	s_cselect_b32 s75, s46, s11
	s_cselect_b32 s74, s21, s10
	s_cselect_b32 s77, s96, s57
	s_cselect_b32 s76, s47, s1
	s_cselect_b32 s73, s97, s72
	s_cselect_b32 s72, s33, s71
	s_cselect_b32 s71, vcc_hi, s80
	s_cselect_b32 s70, vcc_lo, s70
	s_add_i32 s1, s84, 0x100
	v_add_u32_e32 v142, s1, v150
	ds_read_b128 v[134:137], v142
	ds_read_b128 v[138:141], v142 offset:1024
	ds_read_b128 v[152:155], v142 offset:2048
	ds_read_b128 v[156:159], v142 offset:3072
	s_add_u32 s10, s9, s0
	s_addc_u32 s11, s19, 0
	v_lshl_add_u64 v[142:143], s[10:11], 0, v[128:129]
	s_add_i32 m0, s15, 0xc000
	ds_read_b128 v[160:163], v151
	ds_read_b128 v[164:167], v151 offset:1024
	ds_read_b128 v[168:171], v151 offset:2048
	ds_read_b128 v[172:175], v151 offset:3072
	ds_read_b128 v[176:179], v151 offset:4096
	ds_read_b128 v[180:183], v151 offset:5120
	ds_read_b128 v[184:187], v151 offset:6144
	ds_read_b128 v[188:191], v151 offset:7168
	global_load_lds_dwordx4 v[142:143], off
	v_lshl_add_u64 v[142:143], s[10:11], 0, v[130:131]
	s_add_i32 m0, s15, 0xe000
	s_nop 0
	global_load_lds_dwordx4 v[142:143], off
	s_waitcnt lgkmcnt(8)
	s_barrier
	s_waitcnt lgkmcnt(0)
	v_mfma_f32_16x16x32_bf16 v[124:127], v[134:137], v[160:163], v[124:127]
	v_mfma_f32_16x16x32_bf16 v[120:123], v[152:155], v[160:163], v[120:123]
	v_mfma_f32_16x16x32_bf16 v[108:111], v[134:137], v[168:171], v[108:111]
	v_mfma_f32_16x16x32_bf16 v[104:107], v[152:155], v[168:171], v[104:107]
	v_mfma_f32_16x16x32_bf16 v[92:95], v[134:137], v[176:179], v[92:95]
	v_mfma_f32_16x16x32_bf16 v[88:91], v[152:155], v[176:179], v[88:91]
	v_mfma_f32_16x16x32_bf16 v[76:79], v[134:137], v[184:187], v[76:79]
	v_mfma_f32_16x16x32_bf16 v[72:75], v[152:155], v[184:187], v[72:75]
	v_mfma_f32_16x16x32_bf16 v[124:127], v[138:141], v[164:167], v[124:127]
	v_mfma_f32_16x16x32_bf16 v[120:123], v[156:159], v[164:167], v[120:123]
	v_mfma_f32_16x16x32_bf16 v[108:111], v[138:141], v[172:175], v[108:111]
	v_mfma_f32_16x16x32_bf16 v[104:107], v[156:159], v[172:175], v[104:107]
	v_mfma_f32_16x16x32_bf16 v[92:95], v[138:141], v[180:183], v[92:95]
	v_mfma_f32_16x16x32_bf16 v[88:91], v[156:159], v[180:183], v[88:91]
	v_mfma_f32_16x16x32_bf16 v[76:79], v[138:141], v[188:191], v[76:79]
	v_mfma_f32_16x16x32_bf16 v[72:75], v[156:159], v[188:191], v[72:75]
	s_barrier
	s_add_i32 s0, s85, 0x100
	v_add_u32_e32 v142, s0, v150
	s_add_i32 s1, s1, s5
	ds_read_b128 v[192:195], v142
	ds_read_b128 v[196:199], v142 offset:1024
	ds_read_b128 v[200:203], v142 offset:2048
	ds_read_b128 v[204:207], v142 offset:3072
	v_lshl_add_u64 v[142:143], s[76:77], 0, v[146:147]
	s_mov_b32 m0, s1
	s_nop 0
	global_load_lds_dwordx4 v[142:143], off
	v_lshl_add_u64 v[142:143], s[76:77], 0, v[132:133]
	s_add_i32 m0, s1, 0x2000
	s_nop 0
	global_load_lds_dwordx4 v[142:143], off
	s_barrier
	s_waitcnt lgkmcnt(0)
	v_mfma_f32_16x16x32_bf16 v[116:119], v[192:195], v[160:163], v[116:119]
	v_mfma_f32_16x16x32_bf16 v[112:115], v[200:203], v[160:163], v[112:115]
	v_mfma_f32_16x16x32_bf16 v[100:103], v[192:195], v[168:171], v[100:103]
	v_mfma_f32_16x16x32_bf16 v[96:99], v[200:203], v[168:171], v[96:99]
	v_mfma_f32_16x16x32_bf16 v[84:87], v[192:195], v[176:179], v[84:87]
	v_mfma_f32_16x16x32_bf16 v[80:83], v[200:203], v[176:179], v[80:83]
	v_mfma_f32_16x16x32_bf16 v[68:71], v[192:195], v[184:187], v[68:71]
	v_mfma_f32_16x16x32_bf16 v[64:67], v[200:203], v[184:187], v[64:67]
	v_mfma_f32_16x16x32_bf16 v[116:119], v[196:199], v[164:167], v[116:119]
	v_mfma_f32_16x16x32_bf16 v[112:115], v[204:207], v[164:167], v[112:115]
	v_mfma_f32_16x16x32_bf16 v[100:103], v[196:199], v[172:175], v[100:103]
	v_mfma_f32_16x16x32_bf16 v[96:99], v[204:207], v[172:175], v[96:99]
	v_mfma_f32_16x16x32_bf16 v[84:87], v[196:199], v[180:183], v[84:87]
	v_mfma_f32_16x16x32_bf16 v[80:83], v[204:207], v[180:183], v[80:83]
	v_mfma_f32_16x16x32_bf16 v[68:71], v[196:199], v[188:191], v[68:71]
	v_mfma_f32_16x16x32_bf16 v[64:67], v[204:207], v[188:191], v[64:67]
	s_mov_b32 m0, s15
	v_lshl_add_u64 v[142:143], s[74:75], 0, v[128:129]
	s_barrier
	ds_read_b128 v[160:163], v151 offset:16384
	ds_read_b128 v[164:167], v151 offset:17408
	ds_read_b128 v[168:171], v151 offset:18432
	ds_read_b128 v[172:175], v151 offset:19456
	ds_read_b128 v[176:179], v151 offset:20480
	ds_read_b128 v[180:183], v151 offset:21504
	ds_read_b128 v[184:187], v151 offset:22528
	ds_read_b128 v[188:191], v151 offset:23552
	global_load_lds_dwordx4 v[142:143], off
	v_lshl_add_u64 v[142:143], s[74:75], 0, v[130:131]
	s_mov_b32 m0, s24
	s_nop 0
	global_load_lds_dwordx4 v[142:143], off
	s_barrier
	s_waitcnt lgkmcnt(0)
	v_mfma_f32_16x16x32_bf16 v[60:63], v[134:137], v[160:163], v[60:63]
	v_mfma_f32_16x16x32_bf16 v[56:59], v[152:155], v[160:163], v[56:59]
	v_mfma_f32_16x16x32_bf16 v[44:47], v[134:137], v[168:171], v[44:47]
	v_mfma_f32_16x16x32_bf16 v[40:43], v[152:155], v[168:171], v[40:43]
	v_mfma_f32_16x16x32_bf16 v[28:31], v[134:137], v[176:179], v[28:31]
	v_mfma_f32_16x16x32_bf16 v[24:27], v[152:155], v[176:179], v[24:27]
	v_mfma_f32_16x16x32_bf16 v[12:15], v[134:137], v[184:187], v[12:15]
	v_mfma_f32_16x16x32_bf16 v[8:11], v[152:155], v[184:187], v[8:11]
	v_mfma_f32_16x16x32_bf16 v[60:63], v[138:141], v[164:167], v[60:63]
	v_mfma_f32_16x16x32_bf16 v[56:59], v[156:159], v[164:167], v[56:59]
	v_mfma_f32_16x16x32_bf16 v[44:47], v[138:141], v[172:175], v[44:47]
	v_mfma_f32_16x16x32_bf16 v[40:43], v[156:159], v[172:175], v[40:43]
	v_mfma_f32_16x16x32_bf16 v[28:31], v[138:141], v[180:183], v[28:31]
	v_mfma_f32_16x16x32_bf16 v[24:27], v[156:159], v[180:183], v[24:27]
	v_mfma_f32_16x16x32_bf16 v[12:15], v[138:141], v[188:191], v[12:15]
	v_mfma_f32_16x16x32_bf16 v[8:11], v[156:159], v[188:191], v[8:11]
	s_barrier
; #define G_STAGE(bufoff, gbase, voff) do { _Pragma("unroll") for (int _i = 0; _i < 2; ++_i) \
;         __builtin_amdgcn_global_load_lds((const unsigned*)((const char*)(gbase) + (voff)[_i]), (LAS unsigned*)(lds + (bufoff) + ldsw + _i * 8192), 16, 0, 0); } while (0)
; #define G_LDA(dst, b, h) do { _Pragma("unroll") for (int m = 0; m < 4; ++m) _Pragma("unroll") for (int k = 0; k < 2; ++k) dst[m][k] = *(const LAS bf16x8*)(lds + G_SA(b, h) + aoff + m * 2048 + k * 1024); } while (0)
; #define G_LDB(dst, b, h) do { _Pragma("unroll") for (int n = 0; n < 2; ++n) _Pragma("unroll") for (int k = 0; k < 2; ++k) dst[n][k] = *(const LAS bf16x8*)(lds + G_SB(b, h) + boff + n * 2048 + k * 1024); } while (0)
; #define G_MMA(ai, bj, At, Bt) do { __builtin_amdgcn_s_setprio(1); _Pragma("unroll") for (int m = 0; m < 4; ++m) _Pragma("unroll") for (int n = 0; n < 2; ++n) _Pragma("unroll") for (int k = 0; k < 2; ++k) \
;         acc[ai][bj][m][n] = __builtin_amdgcn_mfma_f32_16x16x32_bf16(Bt[n][k], At[m][k], acc[ai][bj][m][n], 0, 0, 0); __builtin_amdgcn_s_setprio(0); } while (0)
; #define G_WAIT_V(n) asm volatile("s_waitcnt vmcnt(" #n ")" ::: "memory")
; #define G_WAIT_L(n) asm volatile("s_waitcnt lgkmcnt(" #n ")" ::: "memory")
; #define G_BAR __builtin_amdgcn_s_barrier()
; #define G_SCHED __builtin_amdgcn_sched_barrier(0)
; template <class J>
; DI void gemm_phase(LAS unsigned char* lds, const J& job) {
;     ...
;       G_STAGE(G_SB(0, 1), b2 + hstepB, voffB);
;       G_WAIT_V(6); G_BAR; G_MMA(1, 1, At, B1); G_BAR;
;       G_LDB(B0, 1, 0); G_SCHED; G_LDA(At, 1, 0); G_STAGE(G_SA(0, 1), a2 + hstepA, voffA);
;       G_WAIT_L(8); G_BAR; G_WAIT_L(0); G_MMA(0, 0, At, B0); G_BAR; G_SCHED;
;       G_LDB(B1, 1, 1); G_STAGE(G_SB(1, 0), b3, voffB);
;       G_BAR; G_WAIT_L(0); G_MMA(0, 1, At, B1); G_BAR;
;       G_LDA(At, 1, 1); G_STAGE(G_SA(1, 0), a3, voffA);
;       G_BAR; G_WAIT_L(0); G_MMA(1, 0, At, B0); G_BAR; G_SCHED;
	s_add_u32 s10, s76, 0x80000
	s_addc_u32 s11, s77, 0
	s_add_i32 s0, s0, s5
	v_lshl_add_u64 v[134:135], s[10:11], 0, v[146:147]
	s_mov_b32 m0, s0
	s_nop 0
	global_load_lds_dwordx4 v[134:135], off
	v_lshl_add_u64 v[134:135], s[10:11], 0, v[132:133]
	s_add_i32 m0, s0, 0x2000
	s_nop 0
	global_load_lds_dwordx4 v[134:135], off
	s_waitcnt vmcnt(6)
	s_barrier
	v_mfma_f32_16x16x32_bf16 v[52:55], v[192:195], v[160:163], v[52:55]
	v_mfma_f32_16x16x32_bf16 v[48:51], v[200:203], v[160:163], v[48:51]
	v_mfma_f32_16x16x32_bf16 v[36:39], v[192:195], v[168:171], v[36:39]
	v_mfma_f32_16x16x32_bf16 v[32:35], v[200:203], v[168:171], v[32:35]
	v_mfma_f32_16x16x32_bf16 v[20:23], v[192:195], v[176:179], v[20:23]
	v_mfma_f32_16x16x32_bf16 v[16:19], v[200:203], v[176:179], v[16:19]
	v_mfma_f32_16x16x32_bf16 v[4:7], v[192:195], v[184:187], v[4:7]
	v_mfma_f32_16x16x32_bf16 v[0:3], v[200:203], v[184:187], v[0:3]
	v_mfma_f32_16x16x32_bf16 v[52:55], v[196:199], v[164:167], v[52:55]
	v_mfma_f32_16x16x32_bf16 v[48:51], v[204:207], v[164:167], v[48:51]
	v_mfma_f32_16x16x32_bf16 v[36:39], v[196:199], v[172:175], v[36:39]
	v_mfma_f32_16x16x32_bf16 v[32:35], v[204:207], v[172:175], v[32:35]
	v_mfma_f32_16x16x32_bf16 v[20:23], v[196:199], v[180:183], v[20:23]
	v_mfma_f32_16x16x32_bf16 v[16:19], v[204:207], v[180:183], v[16:19]
	v_mfma_f32_16x16x32_bf16 v[4:7], v[196:199], v[188:191], v[4:7]
	v_mfma_f32_16x16x32_bf16 v[0:3], v[204:207], v[188:191], v[0:3]
	s_add_i32 s0, s88, 0x100
	v_add_u32_e32 v142, s0, v150
	s_barrier
	ds_read_b128 v[134:137], v142
	ds_read_b128 v[138:141], v142 offset:1024
	ds_read_b128 v[152:155], v142 offset:2048
	ds_read_b128 v[156:159], v142 offset:3072
	s_add_u32 s10, s74, 0x80000
	s_addc_u32 s11, s75, 0
	s_mov_b32 m0, s25
	v_lshl_add_u64 v[142:143], s[10:11], 0, v[128:129]
	ds_read_b128 v[160:163], v151 offset:32768
	ds_read_b128 v[164:167], v151 offset:33792
	ds_read_b128 v[168:171], v151 offset:34816
	ds_read_b128 v[172:175], v151 offset:35840
	ds_read_b128 v[176:179], v151 offset:36864
	ds_read_b128 v[180:183], v151 offset:37888
	ds_read_b128 v[184:187], v151 offset:38912
	ds_read_b128 v[188:191], v151 offset:39936
	global_load_lds_dwordx4 v[142:143], off
	v_lshl_add_u64 v[142:143], s[10:11], 0, v[130:131]
	s_mov_b32 m0, s36
	s_nop 0
	global_load_lds_dwordx4 v[142:143], off
	s_waitcnt lgkmcnt(8)
	s_barrier
	s_waitcnt lgkmcnt(0)
	v_mfma_f32_16x16x32_bf16 v[124:127], v[134:137], v[160:163], v[124:127]
	v_mfma_f32_16x16x32_bf16 v[120:123], v[152:155], v[160:163], v[120:123]
	v_mfma_f32_16x16x32_bf16 v[108:111], v[134:137], v[168:171], v[108:111]
	v_mfma_f32_16x16x32_bf16 v[104:107], v[152:155], v[168:171], v[104:107]
	v_mfma_f32_16x16x32_bf16 v[92:95], v[134:137], v[176:179], v[92:95]
	v_mfma_f32_16x16x32_bf16 v[88:91], v[152:155], v[176:179], v[88:91]
	v_mfma_f32_16x16x32_bf16 v[76:79], v[134:137], v[184:187], v[76:79]
	v_mfma_f32_16x16x32_bf16 v[72:75], v[152:155], v[184:187], v[72:75]
	v_mfma_f32_16x16x32_bf16 v[124:127], v[138:141], v[164:167], v[124:127]
	v_mfma_f32_16x16x32_bf16 v[120:123], v[156:159], v[164:167], v[120:123]
	v_mfma_f32_16x16x32_bf16 v[108:111], v[138:141], v[172:175], v[108:111]
	v_mfma_f32_16x16x32_bf16 v[104:107], v[156:159], v[172:175], v[104:107]
	v_mfma_f32_16x16x32_bf16 v[92:95], v[138:141], v[180:183], v[92:95]
	v_mfma_f32_16x16x32_bf16 v[88:91], v[156:159], v[180:183], v[88:91]
	v_mfma_f32_16x16x32_bf16 v[76:79], v[138:141], v[188:191], v[76:79]
	v_mfma_f32_16x16x32_bf16 v[72:75], v[156:159], v[188:191], v[72:75]
	s_barrier
	s_add_i32 s1, s89, 0x100
	v_add_u32_e32 v142, s1, v150
	s_add_i32 s0, s0, s5
	ds_read_b128 v[192:195], v142
	ds_read_b128 v[196:199], v142 offset:1024
	ds_read_b128 v[200:203], v142 offset:2048
	ds_read_b128 v[204:207], v142 offset:3072
	v_lshl_add_u64 v[142:143], s[70:71], 0, v[146:147]
	s_mov_b32 m0, s0
	s_nop 0
	global_load_lds_dwordx4 v[142:143], off
	v_lshl_add_u64 v[142:143], s[70:71], 0, v[132:133]
	s_add_i32 m0, s0, 0x2000
	s_nop 0
	global_load_lds_dwordx4 v[142:143], off
	s_barrier
	s_waitcnt lgkmcnt(0)
	v_mfma_f32_16x16x32_bf16 v[116:119], v[192:195], v[160:163], v[116:119]
	v_mfma_f32_16x16x32_bf16 v[112:115], v[200:203], v[160:163], v[112:115]
	v_mfma_f32_16x16x32_bf16 v[100:103], v[192:195], v[168:171], v[100:103]
	v_mfma_f32_16x16x32_bf16 v[96:99], v[200:203], v[168:171], v[96:99]
	v_mfma_f32_16x16x32_bf16 v[84:87], v[192:195], v[176:179], v[84:87]
	v_mfma_f32_16x16x32_bf16 v[80:83], v[200:203], v[176:179], v[80:83]
	v_mfma_f32_16x16x32_bf16 v[68:71], v[192:195], v[184:187], v[68:71]
	v_mfma_f32_16x16x32_bf16 v[64:67], v[200:203], v[184:187], v[64:67]
	v_mfma_f32_16x16x32_bf16 v[116:119], v[196:199], v[164:167], v[116:119]
	v_mfma_f32_16x16x32_bf16 v[112:115], v[204:207], v[164:167], v[112:115]
	v_mfma_f32_16x16x32_bf16 v[100:103], v[196:199], v[172:175], v[100:103]
	v_mfma_f32_16x16x32_bf16 v[96:99], v[204:207], v[172:175], v[96:99]
	v_mfma_f32_16x16x32_bf16 v[84:87], v[196:199], v[180:183], v[84:87]
	v_mfma_f32_16x16x32_bf16 v[80:83], v[204:207], v[180:183], v[80:83]
	v_mfma_f32_16x16x32_bf16 v[68:71], v[196:199], v[188:191], v[68:71]
	v_mfma_f32_16x16x32_bf16 v[64:67], v[204:207], v[188:191], v[64:67]
	s_mov_b32 m0, s45
	v_lshl_add_u64 v[142:143], s[72:73], 0, v[128:129]
	s_barrier
; DI unsigned pk2(float lo, float hi) { unsigned r; asm("v_cvt_pk_bf16_f32 %0, %1, %2" : "=v"(r) : "v"(lo), "v"(hi)); return r; }
; #define G_STAGE(bufoff, gbase, voff) do { _Pragma("unroll") for (int _i = 0; _i < 2; ++_i) \
;         __builtin_amdgcn_global_load_lds((const unsigned*)((const char*)(gbase) + (voff)[_i]), (LAS unsigned*)(lds + (bufoff) + ldsw + _i * 8192), 16, 0, 0); } while (0)
; #define G_LDA(dst, b, h) do { _Pragma("unroll") for (int m = 0; m < 4; ++m) _Pragma("unroll") for (int k = 0; k < 2; ++k) dst[m][k] = *(const LAS bf16x8*)(lds + G_SA(b, h) + aoff + m * 2048 + k * 1024); } while (0)
; #define G_MMA(ai, bj, At, Bt) do { __builtin_amdgcn_s_setprio(1); _Pragma("unroll") for (int m = 0; m < 4; ++m) _Pragma("unroll") for (int n = 0; n < 2; ++n) _Pragma("unroll") for (int k = 0; k < 2; ++k) \
;         acc[ai][bj][m][n] = __builtin_amdgcn_mfma_f32_16x16x32_bf16(Bt[n][k], At[m][k], acc[ai][bj][m][n], 0, 0, 0); __builtin_amdgcn_s_setprio(0); } while (0)
; #define G_WAIT_V(n) asm volatile("s_waitcnt vmcnt(" #n ")" ::: "memory")
; #define G_WAIT_L(n) asm volatile("s_waitcnt lgkmcnt(" #n ")" ::: "memory")
; #define G_BAR __builtin_amdgcn_s_barrier()
; #define G_SCHED __builtin_amdgcn_sched_barrier(0)
; template <class J>
; DI void gemm_phase(LAS unsigned char* lds, const J& job) {
;     ...
;       G_LDA(At, 1, 1); G_STAGE(G_SA(1, 0), a3, voffA);
;       G_BAR; G_WAIT_L(0); G_MMA(1, 0, At, B0); G_BAR; G_SCHED;
;       G_STAGE(G_SB(1, 1), b3 + hstepB, voffB);
;       G_WAIT_V(6); G_BAR; G_MMA(1, 1, At, B1); G_BAR;
;   DI void epi(const Acc& acc, const Unit& u, int wr, int wc, int fr, int fq) const {
;     ...
;         const int rl = ai * HALF + wr * 64 + m * 16 + fr;
; #pragma unroll
;         for (int bj = 0; bj < 2; ++bj) {
;           const int col = u.pn * 256 + bj * HALF + wc * 32 + 8 * fq;
;           const f32x4 v0 = acc[ai][bj][m][0], v1 = acc[ai][bj][m][1];
;           const int row = u.pm * 256 + rl;
;           u32x4 o; o.x = pk2(v0.x, v0.y); o.y = pk2(v0.z, v0.w); o.z = pk2(v1.x, v1.y); o.w = pk2(v1.z, v1.w);
;           *(u32x4*)(proj + (size_t)row * NPROJ + col) = o;
;           if (u.pn >= 8 && u.pn < 12) {
;             const int isv = u.pn >= 10; const int cc = col - (isv ? C_BV : C_BK);
;             float* dst = out + (isv ? O_VP : O_KP) + ((size_t)l * TP + row) * 512 + cc;
;             *(f32x4*)dst = v0; *(f32x4*)(dst + 4) = v1;
	ds_read_b128 v[160:163], v151 offset:49152
	ds_read_b128 v[164:167], v151 offset:50176
	ds_read_b128 v[168:171], v151 offset:51200
	ds_read_b128 v[172:175], v151 offset:52224
	ds_read_b128 v[176:179], v151 offset:53248
	ds_read_b128 v[180:183], v151 offset:54272
	ds_read_b128 v[184:187], v151 offset:55296
	ds_read_b128 v[188:191], v151 offset:56320
	global_load_lds_dwordx4 v[142:143], off
	v_lshl_add_u64 v[142:143], s[72:73], 0, v[130:131]
	s_mov_b32 m0, s65
	s_nop 0
	global_load_lds_dwordx4 v[142:143], off
	s_barrier
	s_waitcnt lgkmcnt(0)
	v_mfma_f32_16x16x32_bf16 v[60:63], v[134:137], v[160:163], v[60:63]
	v_mfma_f32_16x16x32_bf16 v[56:59], v[152:155], v[160:163], v[56:59]
	v_mfma_f32_16x16x32_bf16 v[44:47], v[134:137], v[168:171], v[44:47]
	v_mfma_f32_16x16x32_bf16 v[40:43], v[152:155], v[168:171], v[40:43]
	v_mfma_f32_16x16x32_bf16 v[28:31], v[134:137], v[176:179], v[28:31]
	v_mfma_f32_16x16x32_bf16 v[24:27], v[152:155], v[176:179], v[24:27]
	v_mfma_f32_16x16x32_bf16 v[12:15], v[134:137], v[184:187], v[12:15]
	v_mfma_f32_16x16x32_bf16 v[8:11], v[152:155], v[184:187], v[8:11]
	v_mfma_f32_16x16x32_bf16 v[60:63], v[138:141], v[164:167], v[60:63]
	v_mfma_f32_16x16x32_bf16 v[56:59], v[156:159], v[164:167], v[56:59]
	v_mfma_f32_16x16x32_bf16 v[44:47], v[138:141], v[172:175], v[44:47]
	v_mfma_f32_16x16x32_bf16 v[40:43], v[156:159], v[172:175], v[40:43]
	v_mfma_f32_16x16x32_bf16 v[28:31], v[138:141], v[180:183], v[28:31]
	v_mfma_f32_16x16x32_bf16 v[24:27], v[156:159], v[180:183], v[24:27]
	v_mfma_f32_16x16x32_bf16 v[12:15], v[138:141], v[188:191], v[12:15]
	v_mfma_f32_16x16x32_bf16 v[8:11], v[156:159], v[188:191], v[8:11]
	s_barrier
	s_add_u32 s10, s70, 0x80000
	s_addc_u32 s11, s71, 0
	s_add_i32 s0, s1, s5
	v_lshl_add_u64 v[134:135], s[10:11], 0, v[146:147]
	s_mov_b32 m0, s0
	s_nop 0
	global_load_lds_dwordx4 v[134:135], off
	v_lshl_add_u64 v[134:135], s[10:11], 0, v[132:133]
	s_add_i32 m0, s0, 0x2000
	s_nop 0
	global_load_lds_dwordx4 v[134:135], off
	s_waitcnt vmcnt(6)
	s_barrier
	v_mfma_f32_16x16x32_bf16 v[52:55], v[192:195], v[160:163], v[52:55]
	v_mfma_f32_16x16x32_bf16 v[48:51], v[200:203], v[160:163], v[48:51]
	v_mfma_f32_16x16x32_bf16 v[36:39], v[192:195], v[168:171], v[36:39]
	v_mfma_f32_16x16x32_bf16 v[32:35], v[200:203], v[168:171], v[32:35]
	v_mfma_f32_16x16x32_bf16 v[20:23], v[192:195], v[176:179], v[20:23]
	v_mfma_f32_16x16x32_bf16 v[16:19], v[200:203], v[176:179], v[16:19]
	v_mfma_f32_16x16x32_bf16 v[4:7], v[192:195], v[184:187], v[4:7]
	v_mfma_f32_16x16x32_bf16 v[0:3], v[200:203], v[184:187], v[0:3]
	v_mfma_f32_16x16x32_bf16 v[52:55], v[196:199], v[164:167], v[52:55]
	v_mfma_f32_16x16x32_bf16 v[48:51], v[204:207], v[164:167], v[48:51]
	v_mfma_f32_16x16x32_bf16 v[36:39], v[196:199], v[172:175], v[36:39]
	v_mfma_f32_16x16x32_bf16 v[32:35], v[204:207], v[172:175], v[32:35]
	v_mfma_f32_16x16x32_bf16 v[20:23], v[196:199], v[180:183], v[20:23]
	v_mfma_f32_16x16x32_bf16 v[16:19], v[204:207], v[180:183], v[16:19]
	v_mfma_f32_16x16x32_bf16 v[4:7], v[196:199], v[188:191], v[4:7]
	v_mfma_f32_16x16x32_bf16 v[0:3], v[204:207], v[188:191], v[0:3]
	s_add_i32 s6, s6, 2
	s_addk_i32 s56, 0x100
	s_addk_i32 s7, 0x100
	s_cmp_gt_u32 s6, 29
	s_barrier
	s_cbranch_scc0 .LBB0_282
	v_mov_b32_e32 v135, v148
	v_mov_b32_e32 v134, v149
	s_lshl_b32 s0, s64, 8
	s_or_b32 s0, s0, s38
	v_lshl_add_u32 v134, v134, 3, s0
	s_lshl_b32 s0, s8, 8
	s_add_i32 s0, s0, s37
	v_add_u32_e32 v136, s0, v135
	s_and_b32 s0, s64, -4
	s_cmp_eq_u32 s0, 8
	s_cselect_b64 s[66:67], -1, 0
	s_cmp_gt_u32 s64, 9
	s_cselect_b64 s[6:7], -1, 0
	s_and_b64 s[6:7], s[6:7], exec
	s_movk_i32 s1, 0xf600
	v_mov_b64_e32 v[138:139], s[26:27]
	s_cselect_b32 s7, s1, 0xfffff800
	s_mov_b32 s1, 0x3040000
	v_ashrrev_i32_e32 v137, 31, v136
	v_mad_i64_i32 v[138:139], s[8:9], v136, s92, v[138:139]
	v_ashrrev_i32_e32 v135, 31, v134
	s_cselect_b32 s6, s1, 0x2040000
	s_cmp_lg_u32 s0, 8
	v_lshlrev_b64 v[140:141], 11, v[136:137]
	v_lshl_add_u64 v[142:143], v[134:135], 1, v[138:139]
	v_add_u32_e32 v138, s7, v134
	v_cvt_pk_bf16_f32 v152, v124, v125
	v_cvt_pk_bf16_f32 v153, v126, v127
	v_cvt_pk_bf16_f32 v154, v120, v121
	v_cvt_pk_bf16_f32 v155, v122, v123
	global_store_dwordx4 v[142:143], v[152:155], off
	s_cbranch_scc1 .LBB0_285
	s_lshl_b32 s0, s6, 2
	s_add_u32 s8, s83, s0
	s_addc_u32 s9, s86, 0
	v_lshl_add_u64 v[152:153], s[8:9], 0, v[140:141]
	v_ashrrev_i32_e32 v139, 31, v138
	v_lshl_add_u64 v[152:153], v[138:139], 2, v[152:153]
	global_store_dwordx4 v[152:153], v[124:127], off
	global_store_dwordx4 v[152:153], v[120:123], off offset:16
